# modulate_rows: all per-segment g/shift/scale vector loads hoisted ahead of the row-sum reduction (one wait per trip)
# baseline (speedup 1.0000x reference)
.LBB0_202:
	v_add_u32_e32 v0, s16, v36
	v_cmp_gt_i32_e32 vcc, s13, v0
	s_nop 1
	v_cndmask_b32_e32 v54, v36, v0, vcc
	v_mul_hi_i32 v0, v54, s9
	v_lshrrev_b32_e32 v1, 31, v0
	v_ashrrev_i32_e32 v0, 11, v0
	v_add_u32_e32 v2, v0, v1
	v_mad_i32_i24 v4, v2, s18, v54
	v_cmp_lt_i32_e32 vcc, s19, v4
	v_ashrrev_i32_e32 v3, 31, v2
	s_and_saveexec_b64 s[2:3], vcc
	s_xor_b64 s[2:3], exec, s[2:3]
	v_add_u32_e32 v0, 0xffffff00, v4
	v_mov_b32_e32 v1, v41
	v_lshlrev_b64 v[4:5], 24, v[2:3]
	v_lshl_add_u64 v[4:5], s[52:53], 0, v[4:5]
	v_lshlrev_b64 v[0:1], 12, v[0:1]
	v_lshl_add_u64 v[0:1], v[4:5], 0, v[0:1]
	v_mul_hi_i32_i24_e32 v61, 0x1800, v2
	v_mul_i32_i24_e32 v60, 0x1800, v2
	s_andn2_saveexec_b64 s[2:3], s[2:3]
	v_ashrrev_i32_e32 v5, 31, v4
	v_lshlrev_b64 v[0:1], 20, v[2:3]
	v_lshl_add_u64 v[0:1], s[56:57], 0, v[0:1]
	v_lshlrev_b64 v[2:3], 12, v[4:5]
	v_lshl_add_u64 v[0:1], v[0:1], 0, v[2:3]
	v_mov_b64_e32 v[60:61], 0xc000
	s_or_b64 exec, exec, s[2:3]
	v_lshl_add_u64 v[4:5], v[0:1], 0, v[40:41]
	global_load_dwordx4 v[24:27], v[4:5], off nt
	global_load_dwordx4 v[16:19], v[4:5], off offset:1024 nt
	global_load_dwordx4 v[0:3], v[4:5], off offset:3072 nt
	global_load_dwordx4 v[8:11], v[4:5], off offset:2048 nt
	v_mul_hi_i32 v4, v36, s9
	v_lshrrev_b32_e32 v5, 31, v4
	v_ashrrev_i32_e32 v4, 11, v4
	v_add_u32_e32 v56, v4, v5
	v_mad_i32_i24 v6, v56, s18, v36
	v_add_u32_e32 v12, 0xffffff00, v6
	v_cmp_gt_i32_e32 vcc, s17, v6
	v_ashrrev_i32_e32 v57, 31, v56
	v_ashrrev_i32_e32 v7, 31, v6
	v_cndmask_b32_e32 v6, v12, v6, vcc
	v_cndmask_b32_e64 v12, 24, 20, vcc
	v_cndmask_b32_e32 v5, v37, v69, vcc
	v_cndmask_b32_e32 v4, v70, v71, vcc
	v_cndmask_b32_e32 v7, 0, v7, vcc
	v_lshlrev_b64 v[12:13], v12, v[56:57]
	v_lshlrev_b64 v[6:7], 12, v[6:7]
	v_lshl_add_u64 v[4:5], v[4:5], 0, v[12:13]
	v_lshl_add_u64 v[4:5], v[4:5], 0, v[6:7]
	v_lshl_add_u64 v[12:13], v[4:5], 0, v[40:41]
	global_load_dwordx4 v[28:31], v[12:13], off nt
	global_load_dwordx4 v[20:23], v[12:13], off offset:1024 nt
	global_load_dwordx4 v[4:7], v[12:13], off offset:3072 nt
	s_nop 0
	global_load_dwordx4 v[12:15], v[12:13], off offset:2048 nt
	s_nop 0
	global_load_dwordx4 v[32:35], v[42:43], off
	v_cndmask_b32_e64 v55, v56, 8, vcc
	v_mul_hi_i32_i24_e32 v57, 0x6000, v55
	v_mul_i32_i24_e32 v56, 0x6000, v55
	v_lshl_add_u64 v[56:57], s[88:89], 0, v[56:57]
	v_lshl_add_u64 v[58:59], v[56:57], 0, s[36:37]
	v_lshl_add_u64 v[56:57], v[56:57], 0, v[40:41]
	v_lshl_add_u64 v[62:63], v[58:59], 0, v[40:41]
	global_load_dwordx4 v[72:75], v[56:57], off
	global_load_dwordx4 v[64:67], v[62:63], off
	v_cmp_ne_u32_e32 vcc, v36, v54
	v_lshl_add_u64 v[60:61], v[60:61], 2, s[88:89]
	s_waitcnt vmcnt(10)
	v_pk_mul_f32 v[62:63], v[26:27], v[26:27]
	v_pk_mul_f32 v[76:77], v[24:25], v[24:25]
	s_waitcnt vmcnt(9)
	v_pk_mul_f32 v[78:79], v[18:19], v[18:19]
	v_pk_mul_f32 v[80:81], v[16:17], v[16:17]
	v_pk_mov_b32 v[86:87], v[76:77], v[62:63] op_sel:[1,0]
	v_mov_b32_e32 v77, v63
	v_pk_mov_b32 v[62:63], v[80:81], v[78:79] op_sel:[1,0]
	v_mov_b32_e32 v81, v79
	s_waitcnt vmcnt(8)
	v_mul_f32_e32 v85, v1, v1
	s_waitcnt vmcnt(7)
	v_mul_f32_e32 v82, v9, v9
	v_mul_f32_e32 v84, v11, v11
	v_pk_add_f32 v[76:77], v[86:87], v[76:77]
	v_pk_add_f32 v[62:63], v[62:63], v[80:81]
	v_mul_f32_e32 v55, v0, v0
	v_mul_f32_e32 v88, v2, v2
	v_mul_f32_e32 v89, v3, v3
	v_pk_fma_f32 v[78:79], v[8:9], v[8:9], v[82:83] op_sel_hi:[1,1,0]
	v_pk_fma_f32 v[82:83], v[10:11], v[10:11], v[84:85] op_sel_hi:[1,1,0]
	v_pk_add_f32 v[76:77], v[76:77], v[76:77] op_sel:[0,1] op_sel_hi:[1,0]
	v_pk_add_f32 v[62:63], v[62:63], v[62:63] op_sel:[0,1] op_sel_hi:[1,0]
	v_mov_b32_e32 v79, v88
	v_mov_b32_e32 v83, v89
	v_mov_b32_e32 v77, v55
	v_mov_b32_e32 v63, v85
	v_pk_add_f32 v[78:79], v[78:79], v[82:83]
	v_pk_add_f32 v[62:63], v[76:77], v[62:63]
	s_waitcnt vmcnt(6)
	v_pk_mul_f32 v[80:81], v[28:29], v[28:29]
	v_pk_add_f32 v[62:63], v[62:63], v[78:79]
	v_pk_mul_f32 v[78:79], v[30:31], v[30:31]
	s_waitcnt vmcnt(5)
	v_pk_mul_f32 v[82:83], v[22:23], v[22:23]
	v_pk_mul_f32 v[84:85], v[20:21], v[20:21]
	v_pk_mov_b32 v[88:89], v[80:81], v[78:79] op_sel:[1,0]
	v_mov_b32_e32 v81, v79
	v_pk_mov_b32 v[78:79], v[84:85], v[82:83] op_sel:[1,0]
	v_mov_b32_e32 v85, v83
	v_mov_b32_e32 v76, v62
	s_waitcnt vmcnt(3)
	v_mul_f32_e32 v62, v13, v13
	v_mul_f32_e32 v86, v15, v15
	v_pk_add_f32 v[80:81], v[88:89], v[80:81]
	v_pk_add_f32 v[78:79], v[78:79], v[84:85]
	v_mul_f32_e32 v55, v4, v4
	v_mul_f32_e32 v77, v5, v5
	v_mul_f32_e32 v90, v6, v6
	v_mul_f32_e32 v91, v7, v7
	v_pk_fma_f32 v[82:83], v[12:13], v[12:13], v[62:63] op_sel_hi:[1,1,0]
	v_pk_fma_f32 v[86:87], v[14:15], v[14:15], v[86:87] op_sel_hi:[1,1,0]
	v_pk_add_f32 v[80:81], v[80:81], v[80:81] op_sel:[0,1] op_sel_hi:[1,0]
	v_pk_add_f32 v[78:79], v[78:79], v[78:79] op_sel:[0,1] op_sel_hi:[1,0]
	v_mov_b32_e32 v83, v90
	v_mov_b32_e32 v87, v91
	v_mov_b32_e32 v81, v55
	v_mov_b32_e32 v79, v77
	v_pk_add_f32 v[82:83], v[82:83], v[86:87]
	v_pk_add_f32 v[78:79], v[80:81], v[78:79]
	v_ashrrev_i32_e32 v55, 31, v54
	v_pk_add_f32 v[78:79], v[78:79], v[82:83]
	v_lshlrev_b64 v[54:55], 11, v[54:55]
	v_mov_b32_e32 v77, v78
	v_mov_b32_e32 v78, v63
	v_pk_add_f32 v[62:63], v[76:77], v[78:79]
	v_lshl_add_u64 v[170:171], v[60:61],0,s[36:37]
	v_lshl_add_u64 v[172:173], v[170:171],0,v[40:41]
	global_load_dwordx4 v[92:95], v[172:173], off
	v_lshl_add_u64 v[170:171], v[60:61],0,v[40:41]
	global_load_dwordx4 v[96:99], v[170:171], off
	global_load_dwordx4 v[100:103], v[42:43], off offset:1024
	v_lshlrev_b32_e32 v170, 2,v44
	v_mov_b32_e32 v171, v41
	v_lshl_add_u64 v[172:173], v[58:59],0,v[170:171]
	global_load_dwordx4 v[104:107], v[172:173], off
	global_load_dwordx4 v[108:111], v[56:57], off offset:1024
	v_lshl_add_u64 v[170:171], v[60:61],0,s[36:37]
	v_lshlrev_b32_e32 v172, 2,v44
	v_mov_b32_e32 v173, v41
	v_lshl_add_u64 v[174:175], v[170:171],0,v[172:173]
	global_load_dwordx4 v[112:115], v[174:175], off
	v_lshl_add_u64 v[170:171], v[60:61],0,v[40:41]
	global_load_dwordx4 v[116:119], v[170:171], off offset:1024
	global_load_dwordx4 v[120:123], v[42:43], off offset:2048
	v_lshlrev_b32_e32 v170, 2,v46
	v_mov_b32_e32 v171, v41
	v_lshl_add_u64 v[172:173], v[58:59],0,v[170:171]
	global_load_dwordx4 v[124:127], v[172:173], off
	global_load_dwordx4 v[128:131], v[56:57], off offset:2048
	v_lshl_add_u64 v[170:171], v[60:61],0,s[36:37]
	v_lshlrev_b32_e32 v172, 2,v46
	v_mov_b32_e32 v173, v41
	v_lshl_add_u64 v[174:175], v[170:171],0,v[172:173]
	global_load_dwordx4 v[132:135], v[174:175], off
	v_lshl_add_u64 v[170:171], v[60:61],0,v[40:41]
	global_load_dwordx4 v[136:139], v[170:171], off offset:2048
	global_load_dwordx4 v[140:143], v[42:43], off offset:3072
	v_lshlrev_b32_e32 v170, 2,v48
	v_mov_b32_e32 v171, v41
	v_lshl_add_u64 v[172:173], v[58:59],0,v[170:171]
	global_load_dwordx4 v[144:147], v[172:173], off
	global_load_dwordx4 v[148:151], v[56:57], off offset:3072
	v_lshl_add_u64 v[170:171], v[60:61],0,s[36:37]
	v_lshlrev_b32_e32 v172, 2,v48
	v_mov_b32_e32 v173, v41
	v_lshl_add_u64 v[174:175], v[170:171],0,v[172:173]
	global_load_dwordx4 v[152:155], v[174:175], off
	v_lshl_add_u64 v[170:171], v[60:61],0,v[40:41]
	global_load_dwordx4 v[156:159], v[170:171], off offset:3072
	ds_bpermute_b32 v77, v39, v63
	ds_bpermute_b32 v76, v39, v62
	v_lshl_add_u64 v[54:55], s[54:55], 0, v[54:55]
	s_waitcnt lgkmcnt(0)
	v_pk_add_f32 v[62:63], v[62:63], v[76:77]
	ds_bpermute_b32 v77, v45, v63
	ds_bpermute_b32 v76, v45, v62
	s_waitcnt lgkmcnt(0)
	v_pk_add_f32 v[62:63], v[62:63], v[76:77]
	ds_bpermute_b32 v77, v47, v63
	ds_bpermute_b32 v76, v47, v62
	s_waitcnt lgkmcnt(0)
	v_pk_add_f32 v[62:63], v[62:63], v[76:77]
	ds_bpermute_b32 v77, v49, v63
	ds_bpermute_b32 v76, v49, v62
	s_waitcnt lgkmcnt(0)
	v_pk_add_f32 v[62:63], v[62:63], v[76:77]
	ds_bpermute_b32 v77, v53, v63
	ds_bpermute_b32 v76, v53, v62
	s_waitcnt lgkmcnt(0)
	v_pk_add_f32 v[76:77], v[62:63], v[76:77]
	ds_bpermute_b32 v79, v68, v77
	ds_bpermute_b32 v78, v68, v76
	v_lshl_add_u64 v[62:63], v[60:61], 0, s[36:37]
	s_waitcnt lgkmcnt(0)
	s_waitcnt vmcnt(0)
	v_pk_add_f32 v[76:77], v[76:77], v[78:79]
	s_nop 0
	v_pk_fma_f32 v[76:77], v[76:77], s[34:35], v[52:53] op_sel_hi:[1,0,0]
	s_nop 0
	v_mul_f32_e32 v78, 0x4b800000, v77
	v_cmp_gt_f32_e64 s[2:3], s20, v77
	v_mul_f32_e32 v79, 0x4b800000, v76
	v_cmp_gt_f32_e64 s[4:5], s20, v76
	v_cndmask_b32_e64 v77, v77, v78, s[2:3]
	v_rsq_f32_e32 v80, v77
	v_cndmask_b32_e64 v76, v76, v79, s[4:5]
	s_waitcnt vmcnt(0)
	v_pk_add_f32 v[78:79], v[64:65], 1.0 op_sel_hi:[1,0]
	v_rsq_f32_e32 v81, v76
	v_mul_f32_e32 v64, 0x45800000, v80
	v_pk_add_f32 v[76:77], v[66:67], 1.0 op_sel_hi:[1,0]
	v_cndmask_b32_e64 v66, v80, v64, s[2:3]
	v_pk_mul_f32 v[28:29], v[28:29], v[66:67] op_sel_hi:[1,0]
	v_pk_mul_f32 v[30:31], v[30:31], v[66:67] op_sel_hi:[1,0]
	v_pk_mul_f32 v[28:29], v[32:33], v[28:29]
	v_pk_mul_f32 v[30:31], v[34:35], v[30:31]
	v_pk_fma_f32 v[28:29], v[78:79], v[28:29], v[72:73]
	v_pk_fma_f32 v[30:31], v[76:77], v[30:31], v[74:75]
	v_bfe_u32 v67, v28, 16, 1
	v_bfe_u32 v72, v29, 16, 1
	v_add3_u32 v28, v28, v67, s21
	v_bfe_u32 v73, v30, 16, 1
	v_add3_u32 v29, v29, v72, s21
	v_lshrrev_b32_e32 v28, 16, v28
	v_add3_u32 v30, v30, v73, s21
	v_and_or_b32 v28, v29, s22, v28
	v_bfe_u32 v29, v31, 16, 1
	v_mul_f32_e32 v65, 0x45800000, v81
	v_lshrrev_b32_e32 v30, 16, v30
	v_add3_u32 v29, v31, v29, s21
	v_cndmask_b32_e64 v64, v81, v65, s[4:5]
	v_and_or_b32 v29, v29, s22, v30
	v_mov_b32_e32 v65, v64
	global_store_dwordx2 v[50:51], v[28:29], off
	v_lshlrev_b32_e32 v28, 1, v38
	s_and_saveexec_b64 s[2:3], vcc
	s_cbranch_execz .LBB0_208
	v_lshl_add_u64 v[30:31], v[62:63], 0, v[40:41]
	v_mov_b64_e32 v[72:73], v[92:93]
	v_mov_b64_e32 v[74:75], v[94:95]
	v_lshl_add_u64 v[30:31], v[60:61], 0, v[40:41]
	v_mov_b64_e32 v[76:77], v[96:97]
	v_mov_b64_e32 v[78:79], v[98:99]
	v_mov_b32_e32 v30, v64
	v_mov_b32_e32 v31, v64
	v_pk_mul_f32 v[24:25], v[24:25], v[64:65]
	v_pk_mul_f32 v[26:27], v[26:27], v[30:31]
	v_pk_mul_f32 v[24:25], v[32:33], v[24:25]
	v_pk_mul_f32 v[26:27], v[34:35], v[26:27]
	v_mov_b32_e32 v29, v41
	s_nop 0
	v_pk_add_f32 v[30:31], v[74:75], 1.0 op_sel_hi:[1,0]
	v_pk_add_f32 v[32:33], v[72:73], 1.0 op_sel_hi:[1,0]
	s_nop 0
	v_pk_fma_f32 v[26:27], v[26:27], v[30:31], v[78:79]
	v_pk_fma_f32 v[24:25], v[24:25], v[32:33], v[76:77]
	v_bfe_u32 v32, v26, 16, 1
	v_bfe_u32 v30, v24, 16, 1
	v_bfe_u32 v31, v25, 16, 1
	v_bfe_u32 v33, v27, 16, 1
	v_add3_u32 v24, v24, v30, s21
	v_add3_u32 v26, v26, v32, s21
	v_add3_u32 v25, v25, v31, s21
	v_add3_u32 v27, v27, v33, s21
	v_lshrrev_b32_e32 v24, 16, v24
	v_lshrrev_b32_e32 v26, 16, v26
	v_and_or_b32 v24, v25, s22, v24
	v_and_or_b32 v25, v27, s22, v26
	v_lshl_add_u64 v[26:27], v[54:55], 0, v[28:29]
	global_store_dwordx2 v[26:27], v[24:25], off
.LBB0_208:
	s_or_b64 exec, exec, s[2:3]
	v_lshlrev_b32_e32 v32, 2, v44
	v_mov_b32_e32 v33, v41
	v_mov_b64_e32 v[24:25], v[100:101]
	v_mov_b64_e32 v[26:27], v[102:103]
	v_lshl_add_u64 v[30:31], v[58:59], 0, v[32:33]
	v_mov_b64_e32 v[72:73], v[104:105]
	v_mov_b64_e32 v[74:75], v[106:107]
	v_mov_b64_e32 v[76:77], v[108:109]
	v_mov_b64_e32 v[78:79], v[110:111]
	v_mov_b32_e32 v67, v66
	v_mov_b32_e32 v30, v66
	v_mov_b32_e32 v31, v66
	v_pk_mul_f32 v[22:23], v[22:23], v[30:31]
	v_pk_mul_f32 v[20:21], v[20:21], v[66:67]
	s_nop 0
	v_pk_mul_f32 v[22:23], v[22:23], v[26:27]
	v_pk_mul_f32 v[20:21], v[20:21], v[24:25]
	s_nop 0
	v_pk_add_f32 v[34:35], v[74:75], 1.0 op_sel_hi:[1,0]
	v_pk_add_f32 v[72:73], v[72:73], 1.0 op_sel_hi:[1,0]
	s_nop 0
	v_pk_fma_f32 v[22:23], v[22:23], v[34:35], v[78:79]
	v_pk_fma_f32 v[20:21], v[20:21], v[72:73], v[76:77]
	v_bfe_u32 v35, v22, 16, 1
	v_bfe_u32 v29, v20, 16, 1
	v_bfe_u32 v34, v21, 16, 1
	v_bfe_u32 v72, v23, 16, 1
	v_add3_u32 v20, v20, v29, s21
	v_add3_u32 v22, v22, v35, s21
	v_add3_u32 v21, v21, v34, s21
	v_add3_u32 v23, v23, v72, s21
	v_lshrrev_b32_e32 v20, 16, v20
	v_lshrrev_b32_e32 v22, 16, v22
	v_and_or_b32 v20, v21, s22, v20
	v_and_or_b32 v21, v23, s22, v22
	global_store_dwordx2 v[50:51], v[20:21], off offset:512
	s_and_saveexec_b64 s[2:3], vcc
	s_cbranch_execz .LBB0_210
	v_lshl_add_u64 v[20:21], v[62:63], 0, v[32:33]
	v_mov_b64_e32 v[20:21], v[112:113]
	v_mov_b64_e32 v[22:23], v[114:115]
	v_lshl_add_u64 v[32:33], v[60:61], 0, v[40:41]
	v_mov_b64_e32 v[32:33], v[116:117]
	v_mov_b64_e32 v[34:35], v[118:119]
	v_mov_b32_e32 v72, v64
	v_mov_b32_e32 v73, v64
	v_pk_mul_f32 v[16:17], v[16:17], v[64:65]
	v_pk_mul_f32 v[18:19], v[18:19], v[72:73]
	v_pk_mul_f32 v[16:17], v[16:17], v[24:25]
	v_pk_mul_f32 v[18:19], v[18:19], v[26:27]
	v_mov_b32_e32 v29, v41
	s_nop 0
	v_pk_add_f32 v[22:23], v[22:23], 1.0 op_sel_hi:[1,0]
	v_pk_add_f32 v[20:21], v[20:21], 1.0 op_sel_hi:[1,0]
	s_nop 0
	v_pk_fma_f32 v[18:19], v[18:19], v[22:23], v[34:35]
	v_pk_fma_f32 v[16:17], v[16:17], v[20:21], v[32:33]
	v_bfe_u32 v22, v18, 16, 1
	v_bfe_u32 v20, v16, 16, 1
	v_bfe_u32 v21, v17, 16, 1
	v_bfe_u32 v23, v19, 16, 1
	v_add3_u32 v16, v16, v20, s21
	v_add3_u32 v18, v18, v22, s21
	v_add3_u32 v17, v17, v21, s21
	v_add3_u32 v19, v19, v23, s21
	v_lshrrev_b32_e32 v16, 16, v16
	v_lshrrev_b32_e32 v18, 16, v18
	v_and_or_b32 v16, v17, s22, v16
	v_and_or_b32 v17, v19, s22, v18
	v_lshl_add_u64 v[18:19], v[54:55], 0, v[28:29]
	global_store_dwordx2 v[18:19], v[16:17], off offset:512
.LBB0_210:
	s_or_b64 exec, exec, s[2:3]
	v_lshlrev_b32_e32 v20, 2, v46
	v_mov_b32_e32 v21, v41
	v_mov_b64_e32 v[16:17], v[120:121]
	v_mov_b64_e32 v[18:19], v[122:123]
	v_lshl_add_u64 v[22:23], v[58:59], 0, v[20:21]
	v_mov_b64_e32 v[22:23], v[124:125]
	v_mov_b64_e32 v[24:25], v[126:127]
	s_nop 0
	v_mov_b64_e32 v[32:33], v[128:129]
	v_mov_b64_e32 v[34:35], v[130:131]
	v_pk_mul_f32 v[14:15], v[14:15], v[30:31]
	v_pk_mul_f32 v[12:13], v[12:13], v[66:67]
	s_nop 0
	v_pk_mul_f32 v[14:15], v[14:15], v[18:19]
	v_pk_mul_f32 v[12:13], v[12:13], v[16:17]
	s_nop 0
	v_pk_add_f32 v[24:25], v[24:25], 1.0 op_sel_hi:[1,0]
	v_pk_add_f32 v[22:23], v[22:23], 1.0 op_sel_hi:[1,0]
	s_nop 0
	v_pk_fma_f32 v[14:15], v[14:15], v[24:25], v[34:35]
	v_pk_fma_f32 v[12:13], v[12:13], v[22:23], v[32:33]
	v_bfe_u32 v24, v14, 16, 1
	v_bfe_u32 v22, v12, 16, 1
	v_bfe_u32 v23, v13, 16, 1
	v_bfe_u32 v25, v15, 16, 1
	v_add3_u32 v12, v12, v22, s21
	v_add3_u32 v14, v14, v24, s21
	v_add3_u32 v13, v13, v23, s21
	v_add3_u32 v15, v15, v25, s21
	v_lshrrev_b32_e32 v12, 16, v12
	v_lshrrev_b32_e32 v14, 16, v14
	v_and_or_b32 v12, v13, s22, v12
	v_and_or_b32 v13, v15, s22, v14
	global_store_dwordx2 v[50:51], v[12:13], off offset:1024
	s_and_saveexec_b64 s[2:3], vcc
	s_cbranch_execz .LBB0_212
	v_lshl_add_u64 v[12:13], v[62:63], 0, v[20:21]
	v_mov_b64_e32 v[12:13], v[132:133]
	v_mov_b64_e32 v[14:15], v[134:135]
	v_lshl_add_u64 v[20:21], v[60:61], 0, v[40:41]
	v_mov_b64_e32 v[20:21], v[136:137]
	v_mov_b64_e32 v[22:23], v[138:139]
	v_mov_b32_e32 v24, v64
	v_mov_b32_e32 v25, v64
	v_pk_mul_f32 v[8:9], v[8:9], v[64:65]
	v_pk_mul_f32 v[10:11], v[10:11], v[24:25]
	v_pk_mul_f32 v[8:9], v[8:9], v[16:17]
	v_pk_mul_f32 v[10:11], v[10:11], v[18:19]
	v_mov_b32_e32 v29, v41
	s_nop 0
	v_pk_add_f32 v[14:15], v[14:15], 1.0 op_sel_hi:[1,0]
	v_pk_add_f32 v[12:13], v[12:13], 1.0 op_sel_hi:[1,0]
	s_nop 0
	v_pk_fma_f32 v[10:11], v[10:11], v[14:15], v[22:23]
	v_pk_fma_f32 v[8:9], v[8:9], v[12:13], v[20:21]
	v_bfe_u32 v14, v10, 16, 1
	v_bfe_u32 v12, v8, 16, 1
	v_bfe_u32 v13, v9, 16, 1
	v_bfe_u32 v15, v11, 16, 1
	v_add3_u32 v8, v8, v12, s21
	v_add3_u32 v10, v10, v14, s21
	v_add3_u32 v9, v9, v13, s21
	v_add3_u32 v11, v11, v15, s21
	v_lshrrev_b32_e32 v8, 16, v8
	v_lshrrev_b32_e32 v10, 16, v10
	v_and_or_b32 v8, v9, s22, v8
	v_and_or_b32 v9, v11, s22, v10
	v_lshl_add_u64 v[10:11], v[54:55], 0, v[28:29]
	global_store_dwordx2 v[10:11], v[8:9], off offset:1024
.LBB0_212:
	s_or_b64 exec, exec, s[2:3]
	v_lshlrev_b32_e32 v12, 2, v48
	v_mov_b32_e32 v13, v41
	v_mov_b64_e32 v[8:9], v[140:141]
	v_mov_b64_e32 v[10:11], v[142:143]
	v_lshl_add_u64 v[14:15], v[58:59], 0, v[12:13]
	v_mov_b64_e32 v[14:15], v[144:145]
	v_mov_b64_e32 v[16:17], v[146:147]
	s_nop 0
	v_mov_b64_e32 v[18:19], v[148:149]
	v_mov_b64_e32 v[20:21], v[150:151]
	v_mov_b32_e32 v22, v66
	v_mov_b32_e32 v23, v66
	v_pk_mul_f32 v[4:5], v[4:5], v[66:67]
	v_pk_mul_f32 v[6:7], v[6:7], v[22:23]
	s_nop 0
	v_pk_mul_f32 v[4:5], v[4:5], v[8:9]
	v_pk_mul_f32 v[6:7], v[6:7], v[10:11]
	s_nop 0
	v_pk_add_f32 v[16:17], v[16:17], 1.0 op_sel_hi:[1,0]
	v_pk_add_f32 v[14:15], v[14:15], 1.0 op_sel_hi:[1,0]
	s_nop 0
	v_pk_fma_f32 v[6:7], v[6:7], v[16:17], v[20:21]
	v_pk_fma_f32 v[4:5], v[4:5], v[14:15], v[18:19]
	v_bfe_u32 v16, v6, 16, 1
	v_bfe_u32 v14, v4, 16, 1
	v_bfe_u32 v15, v5, 16, 1
	v_bfe_u32 v17, v7, 16, 1
	v_add3_u32 v4, v4, v14, s21
	v_add3_u32 v6, v6, v16, s21
	v_add3_u32 v5, v5, v15, s21
	v_add3_u32 v7, v7, v17, s21
	v_lshrrev_b32_e32 v4, 16, v4
	v_lshrrev_b32_e32 v6, 16, v6
	v_and_or_b32 v4, v5, s22, v4
	v_and_or_b32 v5, v7, s22, v6
	global_store_dwordx2 v[50:51], v[4:5], off offset:1536
	s_and_saveexec_b64 s[2:3], vcc
	s_cbranch_execz .LBB0_201
	v_lshl_add_u64 v[4:5], v[62:63], 0, v[12:13]
	v_mov_b64_e32 v[4:5], v[152:153]
	v_mov_b64_e32 v[6:7], v[154:155]
	v_lshl_add_u64 v[12:13], v[60:61], 0, v[40:41]
	v_mov_b64_e32 v[12:13], v[156:157]
	v_mov_b64_e32 v[14:15], v[158:159]
	v_mov_b32_e32 v16, v64
	v_mov_b32_e32 v17, v64
	v_pk_mul_f32 v[0:1], v[0:1], v[64:65]
	v_pk_mul_f32 v[2:3], v[2:3], v[16:17]
	v_pk_mul_f32 v[0:1], v[0:1], v[8:9]
	v_pk_mul_f32 v[2:3], v[2:3], v[10:11]
	v_mov_b32_e32 v29, v41
	s_nop 0
	v_pk_add_f32 v[6:7], v[6:7], 1.0 op_sel_hi:[1,0]
	v_pk_add_f32 v[4:5], v[4:5], 1.0 op_sel_hi:[1,0]
	s_nop 0
	v_pk_fma_f32 v[2:3], v[2:3], v[6:7], v[14:15]
	v_pk_fma_f32 v[0:1], v[0:1], v[4:5], v[12:13]
	v_bfe_u32 v6, v2, 16, 1
	v_bfe_u32 v4, v0, 16, 1
	v_bfe_u32 v5, v1, 16, 1
	v_bfe_u32 v7, v3, 16, 1
	v_add3_u32 v0, v0, v4, s21
	v_add3_u32 v2, v2, v6, s21
	v_add3_u32 v1, v1, v5, s21
	v_add3_u32 v3, v3, v7, s21
	v_lshrrev_b32_e32 v0, 16, v0
	v_lshrrev_b32_e32 v2, 16, v2
	v_and_or_b32 v0, v1, s22, v0
	v_and_or_b32 v1, v3, s22, v2
	v_lshl_add_u64 v[2:3], v[54:55], 0, v[28:29]
	global_store_dwordx2 v[2:3], v[0:1], off offset:1536
	s_branch .LBB0_201

.LBB0_968:
	v_add_u32_e32 v0, s33, v44
	v_cmp_gt_i32_e32 vcc, s13, v0
	s_movk_i32 s2, 0xff
	s_nop 0
	v_cndmask_b32_e32 v32, v44, v0, vcc
	v_mul_hi_i32 v0, v32, s9
	v_lshrrev_b32_e32 v1, 31, v0
	v_ashrrev_i32_e32 v0, 11, v0
	v_add_u32_e32 v0, v0, v1
	v_mad_i32_i24 v2, v0, s40, v32
	v_cmp_lt_i32_e32 vcc, s2, v2
	v_ashrrev_i32_e32 v1, 31, v0
	s_and_saveexec_b64 s[2:3], vcc
	s_xor_b64 s[2:3], exec, s[2:3]
	v_add_u32_e32 v2, 0xffffff00, v2
	v_mov_b32_e32 v3, v49
	v_lshlrev_b64 v[4:5], 24, v[0:1]
	v_lshl_add_u64 v[4:5], s[72:73], 0, v[4:5]
	v_lshlrev_b64 v[2:3], 12, v[2:3]
	v_lshl_add_u64 v[4:5], v[4:5], 0, v[2:3]
	v_mul_hi_i32_i24_e32 v35, 0x1800, v0
	v_mul_i32_i24_e32 v34, 0x1800, v0
	s_andn2_saveexec_b64 s[2:3], s[2:3]
	v_ashrrev_i32_e32 v3, 31, v2
	v_lshlrev_b64 v[0:1], 20, v[0:1]
	v_lshl_add_u64 v[0:1], s[10:11], 0, v[0:1]
	v_lshlrev_b64 v[2:3], 12, v[2:3]
	v_lshl_add_u64 v[4:5], v[0:1], 0, v[2:3]
	v_mov_b64_e32 v[34:35], 0xc000
	s_or_b64 exec, exec, s[2:3]
	v_mul_hi_i32 v0, v44, s9
	v_lshrrev_b32_e32 v1, 31, v0
	v_ashrrev_i32_e32 v0, 11, v0
	v_add_u32_e32 v0, v0, v1
	v_mad_i32_i24 v6, v0, s40, v44
	s_movk_i32 s2, 0x100
	v_cmp_gt_i32_e64 s[2:3], s2, v6
	v_add_u32_e32 v8, 0xffffff00, v6
	v_ashrrev_i32_e32 v1, 31, v0
	v_ashrrev_i32_e32 v7, 31, v6
	v_cndmask_b32_e64 v6, v8, v6, s[2:3]
	v_cndmask_b32_e64 v8, 24, 20, s[2:3]
	v_cndmask_b32_e64 v3, v45, v77, s[2:3]
	v_cndmask_b32_e64 v2, v78, v79, s[2:3]
	v_cndmask_b32_e64 v7, 0, v7, s[2:3]
	v_lshlrev_b64 v[8:9], v8, v[0:1]
	v_lshl_add_u64 v[2:3], v[2:3], 0, v[8:9]
	v_lshlrev_b64 v[6:7], 12, v[6:7]
	v_cndmask_b32_e64 v0, v0, 8, s[2:3]
	v_lshl_add_u64 v[2:3], v[2:3], 0, v[6:7]
	v_mul_hi_i32_i24_e32 v1, 0x6000, v0
	v_mul_i32_i24_e32 v0, 0x6000, v0
	v_lshl_add_u64 v[36:37], s[88:89], 0, v[0:1]
	v_lshl_add_u64 v[0:1], v[2:3], 0, v[48:49]
	global_load_dwordx4 v[28:31], v[0:1], off nt
	global_load_dwordx4 v[16:19], v[0:1], off offset:1024 nt
	global_load_dwordx4 v[8:11], v[0:1], off offset:2048 nt
	s_nop 0
	global_load_dwordx4 v[0:3], v[0:1], off offset:3072 nt
	v_lshl_add_u64 v[4:5], v[4:5], 0, v[48:49]
	global_load_dwordx4 v[24:27], v[4:5], off nt
	global_load_dwordx4 v[20:23], v[4:5], off offset:1024 nt
	global_load_dwordx4 v[12:15], v[4:5], off offset:2048 nt
	s_nop 0
	global_load_dwordx4 v[4:7], v[4:5], off offset:3072 nt
	s_mov_b32 s2, 0x3a800000
	v_lshl_add_u64 v[72:73], v[36:37], 0, s[36:37]
	v_lshl_add_u64 v[74:75], v[36:37], 0, s[38:39]
	v_cmp_ne_u32_e32 vcc, v44, v32
	v_lshl_add_u64 v[34:35], v[34:35], 2, s[88:89]
	v_lshl_add_u64 v[36:37], v[72:73], 0, v[48:49]
	v_lshl_add_u64 v[68:69], v[34:35], 0, s[38:39]
	s_waitcnt vmcnt(0)
	v_pk_mul_f32 v[38:39], v[30:31], v[30:31]
	v_pk_mul_f32 v[40:41], v[28:29], v[28:29]
	v_mul_f32_e32 v33, v0, v0
	v_pk_mov_b32 v[42:43], v[40:41], v[38:39] op_sel:[1,0]
	v_mov_b32_e32 v41, v39
	v_pk_add_f32 v[38:39], v[42:43], v[40:41]
	v_pk_mul_f32 v[40:41], v[26:27], v[26:27]
	v_pk_mul_f32 v[42:43], v[24:25], v[24:25]
	v_pk_add_f32 v[38:39], v[38:39], v[38:39] op_sel:[0,1] op_sel_hi:[1,0]
	v_pk_mov_b32 v[62:63], v[42:43], v[40:41] op_sel:[1,0]
	v_mov_b32_e32 v43, v41
	v_pk_add_f32 v[40:41], v[62:63], v[42:43]
	v_pk_mul_f32 v[42:43], v[18:19], v[18:19]
	v_pk_mul_f32 v[62:63], v[16:17], v[16:17]
	v_mov_b32_e32 v39, v33
	v_pk_mov_b32 v[64:65], v[62:63], v[42:43] op_sel:[1,0]
	v_mov_b32_e32 v63, v43
	v_pk_add_f32 v[42:43], v[64:65], v[62:63]
	v_pk_mul_f32 v[62:63], v[22:23], v[22:23]
	v_pk_mul_f32 v[64:65], v[20:21], v[20:21]
	v_pk_add_f32 v[42:43], v[42:43], v[42:43] op_sel:[0,1] op_sel_hi:[1,0]
	v_pk_mov_b32 v[66:67], v[64:65], v[62:63] op_sel:[1,0]
	v_mov_b32_e32 v65, v63
	v_pk_add_f32 v[62:63], v[66:67], v[64:65]
	v_mul_f32_e32 v64, v1, v1
	v_mov_b32_e32 v43, v64
	v_pk_add_f32 v[38:39], v[38:39], v[42:43]
	v_mul_f32_e32 v42, v9, v9
	v_mul_f32_e32 v65, v2, v2
	v_pk_fma_f32 v[42:43], v[8:9], v[8:9], v[42:43] op_sel_hi:[1,1,0]
	v_mul_f32_e32 v64, v11, v11
	v_mul_f32_e32 v66, v3, v3
	v_mov_b32_e32 v43, v65
	v_pk_fma_f32 v[64:65], v[10:11], v[10:11], v[64:65] op_sel_hi:[1,1,0]
	v_mul_f32_e32 v33, v4, v4
	v_mov_b32_e32 v65, v66
	v_pk_add_f32 v[42:43], v[42:43], v[64:65]
	v_mul_f32_e32 v64, v5, v5
	v_pk_add_f32 v[38:39], v[38:39], v[42:43]
	v_pk_add_f32 v[40:41], v[40:41], v[40:41] op_sel:[0,1] op_sel_hi:[1,0]
	v_pk_add_f32 v[42:43], v[62:63], v[62:63] op_sel:[0,1] op_sel_hi:[1,0]
	v_mov_b32_e32 v41, v33
	v_mov_b32_e32 v43, v64
	v_pk_add_f32 v[40:41], v[40:41], v[42:43]
	v_mul_f32_e32 v42, v13, v13
	v_mul_f32_e32 v62, v15, v15
	v_mul_f32_e32 v65, v6, v6
	v_mul_f32_e32 v66, v7, v7
	v_pk_fma_f32 v[42:43], v[12:13], v[12:13], v[42:43] op_sel_hi:[1,1,0]
	v_pk_fma_f32 v[62:63], v[14:15], v[14:15], v[62:63] op_sel_hi:[1,1,0]
	v_mov_b32_e32 v43, v65
	v_mov_b32_e32 v63, v66
	v_pk_add_f32 v[42:43], v[42:43], v[62:63]
	v_lshl_add_u64 v[66:67], v[34:35], 0, s[36:37]
	v_pk_add_f32 v[40:41], v[40:41], v[42:43]
	v_mov_b32_e32 v43, v38
	v_mov_b32_e32 v42, v40
	v_mov_b32_e32 v38, v41
	v_pk_add_f32 v[38:39], v[42:43], v[38:39]
	v_lshl_add_u64 v[170:171], v[74:75],0,v[48:49]
	global_load_dwordx4 v[80:83], v[170:171], off
	global_load_dwordx4 v[84:87], v[50:51], off
	global_load_dwordx4 v[88:91], v[36:37], off
	v_lshl_add_u64 v[170:171], v[66:67],0,v[48:49]
	global_load_dwordx4 v[92:95], v[170:171], off
	v_lshl_add_u64 v[170:171], v[68:69],0,v[48:49]
	global_load_dwordx4 v[96:99], v[170:171], off
	global_load_dwordx4 v[100:103], v[50:51], off offset:1024
	v_lshlrev_b32_e32 v170, 2,v52
	v_mov_b32_e32 v171, v49
	v_lshl_add_u64 v[172:173], v[74:75],0,v[170:171]
	global_load_dwordx4 v[104:107], v[172:173], off
	v_lshlrev_b32_e32 v170, 2,v52
	v_mov_b32_e32 v171, v49
	v_lshl_add_u64 v[172:173], v[72:73],0,v[170:171]
	global_load_dwordx4 v[108:111], v[172:173], off
	v_lshlrev_b32_e32 v170, 2,v52
	v_mov_b32_e32 v171, v49
	v_lshl_add_u64 v[172:173], v[66:67],0,v[170:171]
	global_load_dwordx4 v[112:115], v[172:173], off
	v_lshlrev_b32_e32 v170, 2,v52
	v_mov_b32_e32 v171, v49
	v_lshl_add_u64 v[170:171], v[68:69],0,v[170:171]
	global_load_dwordx4 v[116:119], v[170:171], off
	global_load_dwordx4 v[120:123], v[50:51], off offset:2048
	v_lshlrev_b32_e32 v170, 2,v54
	v_mov_b32_e32 v171, v49
	v_lshl_add_u64 v[172:173], v[74:75],0,v[170:171]
	global_load_dwordx4 v[124:127], v[172:173], off
	v_lshlrev_b32_e32 v170, 2,v54
	v_mov_b32_e32 v171, v49
	v_lshl_add_u64 v[172:173], v[72:73],0,v[170:171]
	global_load_dwordx4 v[128:131], v[172:173], off
	v_lshlrev_b32_e32 v170, 2,v54
	v_mov_b32_e32 v171, v49
	v_lshl_add_u64 v[172:173], v[66:67],0,v[170:171]
	global_load_dwordx4 v[132:135], v[172:173], off
	v_lshlrev_b32_e32 v170, 2,v54
	v_mov_b32_e32 v171, v49
	v_lshl_add_u64 v[170:171], v[68:69],0,v[170:171]
	global_load_dwordx4 v[136:139], v[170:171], off
	global_load_dwordx4 v[140:143], v[50:51], off offset:3072
	v_lshlrev_b32_e32 v170, 2,v56
	v_mov_b32_e32 v171, v49
	v_lshl_add_u64 v[172:173], v[74:75],0,v[170:171]
	global_load_dwordx4 v[144:147], v[172:173], off
	v_lshlrev_b32_e32 v170, 2,v56
	v_mov_b32_e32 v171, v49
	v_lshl_add_u64 v[172:173], v[72:73],0,v[170:171]
	global_load_dwordx4 v[148:151], v[172:173], off
	v_lshlrev_b32_e32 v170, 2,v56
	v_mov_b32_e32 v171, v49
	v_lshl_add_u64 v[172:173], v[68:69],0,v[170:171]
	global_load_dwordx4 v[152:155], v[172:173], off
	v_lshlrev_b32_e32 v170, 2,v56
	v_mov_b32_e32 v171, v49
	v_lshl_add_u64 v[170:171], v[66:67],0,v[170:171]
	global_load_dwordx4 v[156:159], v[170:171], off
	ds_bpermute_b32 v41, v47, v39
	ds_bpermute_b32 v40, v47, v38
	s_waitcnt lgkmcnt(0)
	v_pk_add_f32 v[38:39], v[38:39], v[40:41]
	ds_bpermute_b32 v41, v53, v39
	ds_bpermute_b32 v40, v53, v38
	s_waitcnt lgkmcnt(0)
	v_pk_add_f32 v[38:39], v[38:39], v[40:41]
	ds_bpermute_b32 v41, v55, v39
	ds_bpermute_b32 v40, v55, v38
	s_waitcnt lgkmcnt(0)
	v_pk_add_f32 v[38:39], v[38:39], v[40:41]
	ds_bpermute_b32 v41, v57, v39
	ds_bpermute_b32 v40, v57, v38
	s_waitcnt lgkmcnt(0)
	v_pk_add_f32 v[38:39], v[38:39], v[40:41]
	ds_bpermute_b32 v41, v61, v39
	ds_bpermute_b32 v40, v61, v38
	s_waitcnt lgkmcnt(0)
	v_pk_add_f32 v[38:39], v[38:39], v[40:41]
	ds_bpermute_b32 v41, v76, v39
	ds_bpermute_b32 v40, v76, v38
	s_waitcnt lgkmcnt(0)
	s_waitcnt vmcnt(0)
	v_pk_add_f32 v[38:39], v[38:39], v[40:41]
	s_nop 0
	v_pk_fma_f32 v[38:39], v[38:39], s[2:3], v[60:61] op_sel_hi:[1,0,0]
	v_lshl_add_u64 v[40:41], v[74:75], 0, v[48:49]
	v_mul_f32_e32 v33, 0x4b800000, v39
	v_cmp_gt_f32_e64 s[4:5], s41, v39
	v_cmp_gt_f32_e64 s[2:3], s41, v38
	v_mov_b64_e32 v[40:41], v[80:81]
	v_mov_b64_e32 v[42:43], v[82:83]
	v_cndmask_b32_e64 v33, v39, v33, s[4:5]
	v_rsq_f32_e32 v33, v33
	s_nop 0
	v_pk_add_f32 v[40:41], v[40:41], 1.0 op_sel_hi:[1,0]
	v_mul_f32_e32 v39, 0x45800000, v33
	v_cndmask_b32_e64 v70, v33, v39, s[4:5]
	v_mul_f32_e32 v33, 0x4b800000, v38
	v_cndmask_b32_e64 v33, v38, v33, s[2:3]
	v_rsq_f32_e32 v33, v33
	v_pk_mul_f32 v[28:29], v[28:29], v[70:71] op_sel_hi:[1,0]
	v_pk_mul_f32 v[30:31], v[30:31], v[70:71] op_sel_hi:[1,0]
	v_pk_add_f32 v[42:43], v[42:43], 1.0 op_sel_hi:[1,0]
	v_mul_f32_e32 v38, 0x45800000, v33
	v_cndmask_b32_e64 v64, v33, v38, s[2:3]
	v_ashrrev_i32_e32 v33, 31, v32
	v_lshlrev_b64 v[32:33], 11, v[32:33]
	v_lshl_add_u64 v[62:63], s[54:55], 0, v[32:33]
	v_mov_b64_e32 v[32:33], v[84:85]
	v_mov_b64_e32 v[34:35], v[86:87]
	v_mov_b32_e32 v65, v64
	v_mov_b64_e32 v[36:37], v[88:89]
	v_mov_b64_e32 v[38:39], v[90:91]
	s_nop 0
	v_pk_mul_f32 v[28:29], v[32:33], v[28:29]
	v_pk_mul_f32 v[30:31], v[34:35], v[30:31]
	s_nop 0
	v_pk_fma_f32 v[28:29], v[40:41], v[28:29], v[36:37]
	v_pk_fma_f32 v[30:31], v[42:43], v[30:31], v[38:39]
	v_bfe_u32 v36, v28, 16, 1
	v_add3_u32 v28, v28, v36, s42
	v_bfe_u32 v36, v29, 16, 1
	v_lshrrev_b32_e32 v28, 16, v28
	v_add3_u32 v29, v29, v36, s42
	v_and_or_b32 v28, v29, s43, v28
	v_bfe_u32 v29, v30, 16, 1
	v_add3_u32 v29, v30, v29, s42
	v_bfe_u32 v30, v31, 16, 1
	v_lshrrev_b32_e32 v29, 16, v29
	v_add3_u32 v30, v31, v30, s42
	v_and_or_b32 v29, v30, s43, v29
	global_store_dwordx2 v[58:59], v[28:29], off
	v_lshlrev_b32_e32 v28, 1, v46
	s_and_saveexec_b64 s[2:3], vcc
	s_cbranch_execz .LBB0_974
	v_lshl_add_u64 v[30:31], v[66:67], 0, v[48:49]
	v_mov_b64_e32 v[36:37], v[92:93]
	v_mov_b64_e32 v[38:39], v[94:95]
	v_lshl_add_u64 v[30:31], v[68:69], 0, v[48:49]
	v_mov_b64_e32 v[40:41], v[96:97]
	v_mov_b64_e32 v[42:43], v[98:99]
	v_pk_mul_f32 v[24:25], v[24:25], v[64:65]
	v_mov_b32_e32 v30, v64
	v_pk_mul_f32 v[24:25], v[32:33], v[24:25]
	v_mov_b32_e32 v31, v64
	v_pk_mul_f32 v[26:27], v[26:27], v[30:31]
	s_nop 0
	v_pk_add_f32 v[32:33], v[40:41], 1.0 op_sel_hi:[1,0]
	s_nop 0
	v_pk_fma_f32 v[24:25], v[24:25], v[32:33], v[36:37]
	v_pk_mul_f32 v[26:27], v[34:35], v[26:27]
	v_bfe_u32 v29, v24, 16, 1
	v_pk_add_f32 v[30:31], v[42:43], 1.0 op_sel_hi:[1,0]
	v_add3_u32 v24, v24, v29, s42
	v_bfe_u32 v29, v25, 16, 1
	v_pk_fma_f32 v[26:27], v[26:27], v[30:31], v[38:39]
	v_lshrrev_b32_e32 v24, 16, v24
	v_add3_u32 v25, v25, v29, s42
	v_and_or_b32 v24, v25, s43, v24
	v_bfe_u32 v25, v26, 16, 1
	v_add3_u32 v25, v26, v25, s42
	v_bfe_u32 v26, v27, 16, 1
	v_lshrrev_b32_e32 v25, 16, v25
	v_add3_u32 v26, v27, v26, s42
	v_mov_b32_e32 v29, v49
	v_and_or_b32 v25, v26, s43, v25
	v_lshl_add_u64 v[26:27], v[62:63], 0, v[28:29]
	global_store_dwordx2 v[26:27], v[24:25], off
.LBB0_974:
	s_or_b64 exec, exec, s[2:3]
	v_lshlrev_b32_e32 v32, 2, v52
	v_mov_b32_e32 v33, v49
	v_lshl_add_u64 v[30:31], v[74:75], 0, v[32:33]
	v_mov_b64_e32 v[24:25], v[100:101]
	v_mov_b64_e32 v[26:27], v[102:103]
	v_mov_b64_e32 v[34:35], v[104:105]
	v_mov_b64_e32 v[36:37], v[106:107]
	v_lshl_add_u64 v[30:31], v[72:73], 0, v[32:33]
	v_mov_b64_e32 v[38:39], v[108:109]
	v_mov_b64_e32 v[40:41], v[110:111]
	v_mov_b32_e32 v71, v70
	v_mov_b32_e32 v30, v70
	v_mov_b32_e32 v31, v70
	v_pk_mul_f32 v[18:19], v[18:19], v[30:31]
	v_pk_mul_f32 v[16:17], v[16:17], v[70:71]
	s_nop 0
	v_pk_mul_f32 v[18:19], v[18:19], v[26:27]
	v_pk_mul_f32 v[16:17], v[16:17], v[24:25]
	s_nop 0
	v_pk_add_f32 v[36:37], v[36:37], 1.0 op_sel_hi:[1,0]
	v_pk_add_f32 v[34:35], v[34:35], 1.0 op_sel_hi:[1,0]
	s_nop 0
	v_pk_fma_f32 v[18:19], v[18:19], v[36:37], v[40:41]
	v_pk_fma_f32 v[16:17], v[16:17], v[34:35], v[38:39]
	v_bfe_u32 v35, v18, 16, 1
	v_bfe_u32 v29, v16, 16, 1
	v_bfe_u32 v34, v17, 16, 1
	v_bfe_u32 v36, v19, 16, 1
	v_add3_u32 v16, v16, v29, s42
	v_add3_u32 v18, v18, v35, s42
	v_add3_u32 v17, v17, v34, s42
	v_add3_u32 v19, v19, v36, s42
	v_lshrrev_b32_e32 v16, 16, v16
	v_lshrrev_b32_e32 v18, 16, v18
	v_and_or_b32 v16, v17, s43, v16
	v_and_or_b32 v17, v19, s43, v18
	global_store_dwordx2 v[58:59], v[16:17], off offset:512
	s_and_saveexec_b64 s[2:3], vcc
	s_cbranch_execz .LBB0_976
	v_lshl_add_u64 v[16:17], v[66:67], 0, v[32:33]
	v_lshl_add_u64 v[32:33], v[68:69], 0, v[32:33]
	v_mov_b64_e32 v[16:17], v[112:113]
	v_mov_b64_e32 v[18:19], v[114:115]
	v_mov_b32_e32 v36, v64
	v_mov_b64_e32 v[32:33], v[116:117]
	v_mov_b64_e32 v[34:35], v[118:119]
	v_mov_b32_e32 v37, v64
	v_pk_mul_f32 v[22:23], v[22:23], v[36:37]
	v_pk_mul_f32 v[20:21], v[20:21], v[64:65]
	v_pk_mul_f32 v[22:23], v[22:23], v[26:27]
	v_pk_mul_f32 v[20:21], v[20:21], v[24:25]
	v_mov_b32_e32 v29, v49
	s_nop 0
	v_pk_add_f32 v[26:27], v[32:33], 1.0 op_sel_hi:[1,0]
	s_nop 0
	v_pk_fma_f32 v[16:17], v[20:21], v[26:27], v[16:17]
	v_pk_add_f32 v[24:25], v[34:35], 1.0 op_sel_hi:[1,0]
	v_bfe_u32 v20, v16, 16, 1
	v_add3_u32 v16, v16, v20, s42
	v_bfe_u32 v20, v17, 16, 1
	v_pk_fma_f32 v[18:19], v[22:23], v[24:25], v[18:19]
	v_lshrrev_b32_e32 v16, 16, v16
	v_add3_u32 v17, v17, v20, s42
	v_and_or_b32 v16, v17, s43, v16
	v_bfe_u32 v17, v18, 16, 1
	v_add3_u32 v17, v18, v17, s42
	v_bfe_u32 v18, v19, 16, 1
	v_lshrrev_b32_e32 v17, 16, v17
	v_add3_u32 v18, v19, v18, s42
	v_and_or_b32 v17, v18, s43, v17
	v_lshl_add_u64 v[18:19], v[62:63], 0, v[28:29]
	global_store_dwordx2 v[18:19], v[16:17], off offset:512
.LBB0_976:
	s_or_b64 exec, exec, s[2:3]
	v_lshlrev_b32_e32 v20, 2, v54
	v_mov_b32_e32 v21, v49
	v_lshl_add_u64 v[22:23], v[74:75], 0, v[20:21]
	v_mov_b64_e32 v[16:17], v[120:121]
	v_mov_b64_e32 v[18:19], v[122:123]
	v_lshl_add_u64 v[26:27], v[72:73], 0, v[20:21]
	v_mov_b64_e32 v[22:23], v[124:125]
	v_mov_b64_e32 v[24:25], v[126:127]
	v_pk_mul_f32 v[10:11], v[10:11], v[30:31]
	v_mov_b64_e32 v[32:33], v[128:129]
	v_mov_b64_e32 v[34:35], v[130:131]
	v_pk_mul_f32 v[8:9], v[8:9], v[70:71]
	s_nop 0
	v_pk_mul_f32 v[10:11], v[10:11], v[18:19]
	v_pk_mul_f32 v[8:9], v[8:9], v[16:17]
	s_nop 0
	v_pk_add_f32 v[24:25], v[24:25], 1.0 op_sel_hi:[1,0]
	v_pk_add_f32 v[22:23], v[22:23], 1.0 op_sel_hi:[1,0]
	s_nop 0
	v_pk_fma_f32 v[10:11], v[10:11], v[24:25], v[34:35]
	v_pk_fma_f32 v[8:9], v[8:9], v[22:23], v[32:33]
	v_bfe_u32 v24, v10, 16, 1
	v_bfe_u32 v22, v8, 16, 1
	v_bfe_u32 v23, v9, 16, 1
	v_bfe_u32 v25, v11, 16, 1
	v_add3_u32 v8, v8, v22, s42
	v_add3_u32 v10, v10, v24, s42
	v_add3_u32 v9, v9, v23, s42
	v_add3_u32 v11, v11, v25, s42
	v_lshrrev_b32_e32 v8, 16, v8
	v_lshrrev_b32_e32 v10, 16, v10
	v_and_or_b32 v8, v9, s43, v8
	v_and_or_b32 v9, v11, s43, v10
	global_store_dwordx2 v[58:59], v[8:9], off offset:1024
	s_and_saveexec_b64 s[2:3], vcc
	s_cbranch_execz .LBB0_978
	v_lshl_add_u64 v[8:9], v[66:67], 0, v[20:21]
	v_lshl_add_u64 v[20:21], v[68:69], 0, v[20:21]
	v_mov_b64_e32 v[8:9], v[132:133]
	v_mov_b64_e32 v[10:11], v[134:135]
	v_mov_b32_e32 v24, v64
	v_mov_b64_e32 v[20:21], v[136:137]
	v_mov_b64_e32 v[22:23], v[138:139]
	v_mov_b32_e32 v25, v64
	v_pk_mul_f32 v[14:15], v[14:15], v[24:25]
	v_pk_mul_f32 v[12:13], v[12:13], v[64:65]
	v_pk_mul_f32 v[14:15], v[14:15], v[18:19]
	v_pk_mul_f32 v[12:13], v[12:13], v[16:17]
	v_mov_b32_e32 v29, v49
	s_nop 0
	v_pk_add_f32 v[18:19], v[20:21], 1.0 op_sel_hi:[1,0]
	s_nop 0
	v_pk_fma_f32 v[8:9], v[12:13], v[18:19], v[8:9]
	v_pk_add_f32 v[16:17], v[22:23], 1.0 op_sel_hi:[1,0]
	v_bfe_u32 v12, v8, 16, 1
	v_add3_u32 v8, v8, v12, s42
	v_bfe_u32 v12, v9, 16, 1
	v_pk_fma_f32 v[10:11], v[14:15], v[16:17], v[10:11]
	v_lshrrev_b32_e32 v8, 16, v8
	v_add3_u32 v9, v9, v12, s42
	v_and_or_b32 v8, v9, s43, v8
	v_bfe_u32 v9, v10, 16, 1
	v_add3_u32 v9, v10, v9, s42
	v_bfe_u32 v10, v11, 16, 1
	v_lshrrev_b32_e32 v9, 16, v9
	v_add3_u32 v10, v11, v10, s42
	v_and_or_b32 v9, v10, s43, v9
	v_lshl_add_u64 v[10:11], v[62:63], 0, v[28:29]
	global_store_dwordx2 v[10:11], v[8:9], off offset:1024
.LBB0_978:
	s_or_b64 exec, exec, s[2:3]
	v_lshlrev_b32_e32 v12, 2, v56
	v_mov_b32_e32 v13, v49
	v_lshl_add_u64 v[14:15], v[74:75], 0, v[12:13]
	v_mov_b64_e32 v[8:9], v[140:141]
	v_mov_b64_e32 v[10:11], v[142:143]
	v_lshl_add_u64 v[18:19], v[72:73], 0, v[12:13]
	v_mov_b64_e32 v[14:15], v[144:145]
	v_mov_b64_e32 v[16:17], v[146:147]
	v_mov_b32_e32 v22, v70
	v_mov_b64_e32 v[18:19], v[148:149]
	v_mov_b64_e32 v[20:21], v[150:151]
	v_mov_b32_e32 v23, v70
	v_pk_mul_f32 v[0:1], v[0:1], v[70:71]
	v_pk_mul_f32 v[2:3], v[2:3], v[22:23]
	s_nop 0
	v_pk_mul_f32 v[0:1], v[0:1], v[8:9]
	v_pk_mul_f32 v[2:3], v[2:3], v[10:11]
	s_nop 0
	v_pk_add_f32 v[16:17], v[16:17], 1.0 op_sel_hi:[1,0]
	v_pk_add_f32 v[14:15], v[14:15], 1.0 op_sel_hi:[1,0]
	s_nop 0
	v_pk_fma_f32 v[2:3], v[2:3], v[16:17], v[20:21]
	v_pk_fma_f32 v[0:1], v[0:1], v[14:15], v[18:19]
	v_bfe_u32 v16, v2, 16, 1
	v_bfe_u32 v14, v0, 16, 1
	v_bfe_u32 v15, v1, 16, 1
	v_bfe_u32 v17, v3, 16, 1
	v_add3_u32 v0, v0, v14, s42
	v_add3_u32 v2, v2, v16, s42
	v_add3_u32 v1, v1, v15, s42
	v_add3_u32 v3, v3, v17, s42
	v_lshrrev_b32_e32 v0, 16, v0
	v_lshrrev_b32_e32 v2, 16, v2
	v_and_or_b32 v0, v1, s43, v0
	v_and_or_b32 v1, v3, s43, v2
	global_store_dwordx2 v[58:59], v[0:1], off offset:1536
	s_and_saveexec_b64 s[2:3], vcc
	s_cbranch_execz .LBB0_967
	v_lshl_add_u64 v[0:1], v[68:69], 0, v[12:13]
	v_mov_b64_e32 v[0:1], v[152:153]
	v_mov_b64_e32 v[2:3], v[154:155]
	v_lshl_add_u64 v[12:13], v[66:67], 0, v[12:13]
	v_mov_b64_e32 v[12:13], v[156:157]
	v_mov_b64_e32 v[14:15], v[158:159]
	v_mov_b32_e32 v16, v64
	v_mov_b32_e32 v17, v64
	v_pk_mul_f32 v[4:5], v[4:5], v[64:65]
	v_pk_mul_f32 v[6:7], v[6:7], v[16:17]
	v_pk_mul_f32 v[4:5], v[4:5], v[8:9]
	v_pk_mul_f32 v[6:7], v[6:7], v[10:11]
	v_mov_b32_e32 v29, v49
	s_nop 0
	v_pk_add_f32 v[2:3], v[2:3], 1.0 op_sel_hi:[1,0]
	v_pk_add_f32 v[0:1], v[0:1], 1.0 op_sel_hi:[1,0]
	s_nop 0
	v_pk_fma_f32 v[2:3], v[6:7], v[2:3], v[14:15]
	v_pk_fma_f32 v[0:1], v[4:5], v[0:1], v[12:13]
	v_bfe_u32 v6, v2, 16, 1
	v_bfe_u32 v4, v0, 16, 1
	v_bfe_u32 v5, v1, 16, 1
	v_bfe_u32 v7, v3, 16, 1
	v_add3_u32 v0, v0, v4, s42
	v_add3_u32 v2, v2, v6, s42
	v_add3_u32 v1, v1, v5, s42
	v_add3_u32 v3, v3, v7, s42
	v_lshrrev_b32_e32 v0, 16, v0
	v_lshrrev_b32_e32 v2, 16, v2
	v_and_or_b32 v0, v1, s43, v0
	v_and_or_b32 v1, v3, s43, v2
	v_lshl_add_u64 v[2:3], v[62:63], 0, v[28:29]
	global_store_dwordx2 v[2:3], v[0:1], off offset:1536
	s_branch .LBB0_967

.LBB0_1449:
	v_add_u32_e32 v0, s36, v36
	v_cmp_gt_i32_e32 vcc, s13, v0
	s_nop 1
	v_cndmask_b32_e32 v60, v36, v0, vcc
	v_mul_hi_i32 v0, v60, s15
	v_lshrrev_b32_e32 v1, 31, v0
	v_ashrrev_i32_e32 v0, 11, v0
	v_add_u32_e32 v2, v0, v1
	v_mad_i32_i24 v4, v2, s21, v60
	v_cmp_lt_i32_e32 vcc, s23, v4
	v_ashrrev_i32_e32 v3, 31, v2
	s_and_saveexec_b64 s[2:3], vcc
	s_xor_b64 s[2:3], exec, s[2:3]
	v_add_u32_e32 v40, 0xffffff00, v4
	v_lshlrev_b64 v[0:1], 24, v[2:3]
	v_lshl_add_u64 v[0:1], s[72:73], 0, v[0:1]
	v_lshlrev_b64 v[4:5], 12, v[40:41]
	v_lshl_add_u64 v[0:1], v[0:1], 0, v[4:5]
	v_mul_hi_i32_i24_e32 v67, 0x1800, v2
	v_mul_i32_i24_e32 v66, 0x1800, v2
	s_andn2_saveexec_b64 s[2:3], s[2:3]
	v_ashrrev_i32_e32 v5, 31, v4
	v_lshlrev_b64 v[0:1], 20, v[2:3]
	v_lshl_add_u64 v[0:1], s[10:11], 0, v[0:1]
	v_lshlrev_b64 v[2:3], 12, v[4:5]
	v_lshl_add_u64 v[0:1], v[0:1], 0, v[2:3]
	v_mov_b64_e32 v[66:67], 0xc000
	s_or_b64 exec, exec, s[2:3]
	v_lshlrev_b32_e32 v40, 2, v38
	v_lshl_add_u64 v[0:1], v[0:1], 0, v[40:41]
	v_mul_hi_i32 v4, v36, s15
	global_load_dwordx4 v[24:27], v[0:1], off nt
	v_lshrrev_b32_e32 v13, 31, v4
	v_ashrrev_i32_e32 v4, 11, v4
	v_add_u32_e32 v62, v4, v13
	global_load_dwordx4 v[16:19], v[0:1], off offset:1024 nt
	global_load_dwordx4 v[8:11], v[0:1], off offset:2048 nt
	s_nop 0
	global_load_dwordx4 v[0:3], v[0:1], off offset:3072 nt
	v_mad_i32_i24 v13, v62, s21, v36
	v_mov_b32_e32 v7, s72
	v_mov_b32_e32 v12, s10
	v_cmp_gt_i32_e32 vcc, s20, v13
	v_mov_b32_e32 v5, s73
	v_mov_b32_e32 v6, s11
	v_ashrrev_i32_e32 v63, 31, v62
	v_add_u32_e32 v14, 0xffffff00, v13
	v_ashrrev_i32_e32 v15, 31, v13
	v_cndmask_b32_e32 v4, v7, v12, vcc
	v_cndmask_b32_e64 v12, 24, 20, vcc
	v_cndmask_b32_e32 v5, v5, v6, vcc
	v_cndmask_b32_e32 v7, 0, v15, vcc
	v_cndmask_b32_e32 v6, v14, v13, vcc
	v_lshlrev_b64 v[12:13], v12, v[62:63]
	v_lshlrev_b64 v[6:7], 12, v[6:7]
	v_lshl_add_u64 v[4:5], v[4:5], 0, v[12:13]
	v_lshl_add_u64 v[4:5], v[4:5], 0, v[6:7]
	v_lshl_add_u64 v[12:13], v[4:5], 0, v[40:41]
	global_load_dwordx4 v[28:31], v[12:13], off nt
	global_load_dwordx4 v[20:23], v[12:13], off offset:1024 nt
	global_load_dwordx4 v[4:7], v[12:13], off offset:3072 nt
	s_nop 0
	global_load_dwordx4 v[12:15], v[12:13], off offset:2048 nt
	s_nop 0
	global_load_dwordx4 v[32:35], v[42:43], off
	v_cndmask_b32_e64 v37, v62, 8, vcc
	v_mul_hi_i32_i24_e32 v63, 0x6000, v37
	v_mul_i32_i24_e32 v62, 0x6000, v37
	v_lshl_add_u64 v[62:63], s[56:57], 0, v[62:63]
	v_lshl_add_u64 v[64:65], v[62:63], 0, s[8:9]
	v_lshl_add_u64 v[62:63], v[62:63], 0, v[40:41]
	v_lshl_add_u64 v[68:69], v[64:65], 0, v[40:41]
	global_load_dwordx4 v[76:79], v[62:63], off
	global_load_dwordx4 v[70:73], v[68:69], off
	v_cmp_ne_u32_e32 vcc, v36, v60
	v_lshl_add_u64 v[66:67], v[66:67], 2, s[56:57]
	s_waitcnt vmcnt(0)
	v_pk_mul_f32 v[68:69], v[26:27], v[26:27]
	v_pk_mul_f32 v[80:81], v[24:25], v[24:25]
	v_pk_mul_f32 v[82:83], v[18:19], v[18:19]
	v_pk_mul_f32 v[84:85], v[16:17], v[16:17]
	v_pk_mov_b32 v[90:91], v[80:81], v[68:69] op_sel:[1,0]
	v_mov_b32_e32 v81, v69
	v_pk_mov_b32 v[68:69], v[84:85], v[82:83] op_sel:[1,0]
	v_mov_b32_e32 v85, v83
	v_mul_f32_e32 v89, v3, v3
	v_mul_f32_e32 v86, v9, v9
	v_mul_f32_e32 v88, v11, v11
	v_pk_add_f32 v[80:81], v[90:91], v[80:81]
	v_pk_add_f32 v[68:69], v[68:69], v[84:85]
	v_mul_f32_e32 v37, v0, v0
	v_mul_f32_e32 v61, v1, v1
	v_mul_f32_e32 v75, v2, v2
	v_pk_fma_f32 v[82:83], v[8:9], v[8:9], v[86:87] op_sel_hi:[1,1,0]
	v_pk_fma_f32 v[86:87], v[10:11], v[10:11], v[88:89] op_sel_hi:[1,1,0]
	v_pk_add_f32 v[80:81], v[80:81], v[80:81] op_sel:[0,1] op_sel_hi:[1,0]
	v_pk_add_f32 v[68:69], v[68:69], v[68:69] op_sel:[0,1] op_sel_hi:[1,0]
	v_mov_b32_e32 v83, v75
	v_mov_b32_e32 v87, v89
	v_mov_b32_e32 v81, v37
	v_mov_b32_e32 v69, v61
	v_pk_add_f32 v[82:83], v[82:83], v[86:87]
	v_pk_add_f32 v[68:69], v[80:81], v[68:69]
	v_pk_mul_f32 v[80:81], v[30:31], v[30:31]
	v_pk_add_f32 v[68:69], v[68:69], v[82:83]
	v_pk_mul_f32 v[82:83], v[28:29], v[28:29]
	v_pk_mul_f32 v[84:85], v[22:23], v[22:23]
	v_pk_mul_f32 v[86:87], v[20:21], v[20:21]
	v_pk_mov_b32 v[92:93], v[82:83], v[80:81] op_sel:[1,0]
	v_mov_b32_e32 v83, v81
	v_pk_mov_b32 v[80:81], v[86:87], v[84:85] op_sel:[1,0]
	v_mov_b32_e32 v87, v85
	v_mul_f32_e32 v91, v7, v7
	v_mul_f32_e32 v88, v13, v13
	v_mul_f32_e32 v90, v15, v15
	v_pk_add_f32 v[82:83], v[92:93], v[82:83]
	v_pk_add_f32 v[80:81], v[80:81], v[86:87]
	v_mul_f32_e32 v37, v4, v4
	v_mul_f32_e32 v61, v5, v5
	v_mul_f32_e32 v75, v6, v6
	v_pk_fma_f32 v[84:85], v[12:13], v[12:13], v[88:89] op_sel_hi:[1,1,0]
	v_pk_fma_f32 v[88:89], v[14:15], v[14:15], v[90:91] op_sel_hi:[1,1,0]
	v_pk_add_f32 v[82:83], v[82:83], v[82:83] op_sel:[0,1] op_sel_hi:[1,0]
	v_pk_add_f32 v[80:81], v[80:81], v[80:81] op_sel:[0,1] op_sel_hi:[1,0]
	v_mov_b32_e32 v85, v75
	v_mov_b32_e32 v89, v91
	v_mov_b32_e32 v83, v37
	v_mov_b32_e32 v81, v61
	v_pk_add_f32 v[84:85], v[84:85], v[88:89]
	v_pk_add_f32 v[80:81], v[82:83], v[80:81]
	v_mov_b32_e32 v82, v68
	v_pk_add_f32 v[80:81], v[80:81], v[84:85]
	v_ashrrev_i32_e32 v61, 31, v60
	v_mov_b32_e32 v83, v80
	v_mov_b32_e32 v80, v69
	v_pk_add_f32 v[68:69], v[82:83], v[80:81]
	v_lshl_add_u64 v[170:171], v[66:67],0,s[8:9]
	v_lshl_add_u64 v[172:173], v[170:171],0,v[40:41]
	global_load_dwordx4 v[94:97], v[172:173], off
	v_lshl_add_u64 v[170:171], v[66:67],0,v[40:41]
	global_load_dwordx4 v[98:101], v[170:171], off
	global_load_dwordx4 v[102:105], v[46:47], off
	v_lshlrev_b32_e32 v170, 2,v44
	v_mov_b32_e32 v171, v41
	v_lshl_add_u64 v[172:173], v[64:65],0,v[170:171]
	global_load_dwordx4 v[106:109], v[172:173], off
	global_load_dwordx4 v[110:113], v[62:63], off offset:1024
	v_lshl_add_u64 v[170:171], v[66:67],0,s[8:9]
	v_lshlrev_b32_e32 v172, 2,v44
	v_mov_b32_e32 v173, v41
	v_lshl_add_u64 v[174:175], v[170:171],0,v[172:173]
	global_load_dwordx4 v[114:117], v[174:175], off
	v_lshl_add_u64 v[170:171], v[66:67],0,v[40:41]
	global_load_dwordx4 v[118:121], v[170:171], off offset:1024
	global_load_dwordx4 v[122:125], v[50:51], off
	v_lshlrev_b32_e32 v170, 2,v48
	v_mov_b32_e32 v171, v41
	v_lshl_add_u64 v[172:173], v[64:65],0,v[170:171]
	global_load_dwordx4 v[126:129], v[172:173], off
	global_load_dwordx4 v[130:133], v[62:63], off offset:2048
	v_lshl_add_u64 v[170:171], v[66:67],0,s[8:9]
	v_lshlrev_b32_e32 v172, 2,v48
	v_mov_b32_e32 v173, v41
	v_lshl_add_u64 v[174:175], v[170:171],0,v[172:173]
	global_load_dwordx4 v[134:137], v[174:175], off
	v_lshl_add_u64 v[170:171], v[66:67],0,v[40:41]
	global_load_dwordx4 v[138:141], v[170:171], off offset:2048
	global_load_dwordx4 v[142:145], v[54:55], off
	v_lshlrev_b32_e32 v170, 2,v52
	v_mov_b32_e32 v171, v41
	v_lshl_add_u64 v[172:173], v[64:65],0,v[170:171]
	global_load_dwordx4 v[146:149], v[172:173], off
	global_load_dwordx4 v[150:153], v[62:63], off offset:3072
	v_lshl_add_u64 v[170:171], v[66:67],0,s[8:9]
	v_lshlrev_b32_e32 v172, 2,v52
	v_mov_b32_e32 v173, v41
	v_lshl_add_u64 v[174:175], v[170:171],0,v[172:173]
	global_load_dwordx4 v[154:157], v[174:175], off
	v_lshl_add_u64 v[170:171], v[66:67],0,v[40:41]
	global_load_dwordx4 v[158:161], v[170:171], off offset:3072
	ds_bpermute_b32 v81, v39, v69
	ds_bpermute_b32 v80, v39, v68
	v_lshlrev_b64 v[60:61], 11, v[60:61]
	v_lshl_add_u64 v[60:61], s[54:55], 0, v[60:61]
	s_waitcnt lgkmcnt(0)
	v_pk_add_f32 v[68:69], v[68:69], v[80:81]
	ds_bpermute_b32 v81, v45, v69
	ds_bpermute_b32 v80, v45, v68
	s_waitcnt lgkmcnt(0)
	v_pk_add_f32 v[68:69], v[68:69], v[80:81]
	ds_bpermute_b32 v81, v49, v69
	ds_bpermute_b32 v80, v49, v68
	s_waitcnt lgkmcnt(0)
	v_pk_add_f32 v[68:69], v[68:69], v[80:81]
	ds_bpermute_b32 v81, v53, v69
	ds_bpermute_b32 v80, v53, v68
	s_waitcnt lgkmcnt(0)
	v_pk_add_f32 v[68:69], v[68:69], v[80:81]
	ds_bpermute_b32 v81, v59, v69
	ds_bpermute_b32 v80, v59, v68
	s_waitcnt lgkmcnt(0)
	v_pk_add_f32 v[80:81], v[68:69], v[80:81]
	ds_bpermute_b32 v83, v74, v81
	ds_bpermute_b32 v82, v74, v80
	v_lshl_add_u64 v[68:69], v[66:67], 0, s[8:9]
	s_waitcnt lgkmcnt(0)
	s_waitcnt vmcnt(0)
	v_pk_add_f32 v[80:81], v[80:81], v[82:83]
	s_nop 0
	v_pk_fma_f32 v[80:81], v[80:81], s[22:23], v[58:59] op_sel_hi:[1,0,0]
	v_pk_add_f32 v[82:83], v[70:71], 1.0 op_sel_hi:[1,0]
	v_mul_f32_e32 v37, 0x4b800000, v81
	v_cmp_gt_f32_e64 s[2:3], s24, v81
	v_mul_f32_e32 v75, 0x4b800000, v80
	v_cmp_gt_f32_e64 s[4:5], s24, v80
	v_cndmask_b32_e64 v37, v81, v37, s[2:3]
	v_rsq_f32_e32 v37, v37
	v_cndmask_b32_e64 v75, v80, v75, s[4:5]
	v_pk_add_f32 v[80:81], v[72:73], 1.0 op_sel_hi:[1,0]
	v_rsq_f32_e32 v75, v75
	v_mul_f32_e32 v70, 0x45800000, v37
	v_cndmask_b32_e64 v72, v37, v70, s[2:3]
	v_pk_mul_f32 v[28:29], v[28:29], v[72:73] op_sel_hi:[1,0]
	v_pk_mul_f32 v[30:31], v[30:31], v[72:73] op_sel_hi:[1,0]
	v_pk_mul_f32 v[28:29], v[32:33], v[28:29]
	v_pk_mul_f32 v[30:31], v[34:35], v[30:31]
	v_pk_fma_f32 v[28:29], v[82:83], v[28:29], v[76:77]
	v_pk_fma_f32 v[30:31], v[80:81], v[30:31], v[78:79]
	v_bfe_u32 v37, v28, 16, 1
	v_add3_u32 v28, v28, v37, s25
	v_bfe_u32 v37, v29, 16, 1
	v_lshrrev_b32_e32 v28, 16, v28
	v_add3_u32 v29, v29, v37, s25
	v_and_or_b32 v28, v29, s26, v28
	v_bfe_u32 v29, v30, 16, 1
	v_add3_u32 v29, v30, v29, s25
	v_bfe_u32 v30, v31, 16, 1
	v_mul_f32_e32 v71, 0x45800000, v75
	v_lshrrev_b32_e32 v29, 16, v29
	v_add3_u32 v30, v31, v30, s25
	v_cndmask_b32_e64 v70, v75, v71, s[4:5]
	v_and_or_b32 v29, v30, s26, v29
	v_mov_b32_e32 v71, v70
	global_store_dwordx2 v[56:57], v[28:29], off
	v_lshlrev_b32_e32 v28, 1, v38
	s_and_saveexec_b64 s[2:3], vcc
	s_cbranch_execz .LBB0_1455
	v_lshl_add_u64 v[30:31], v[68:69], 0, v[40:41]
	v_mov_b64_e32 v[76:77], v[94:95]
	v_mov_b64_e32 v[78:79], v[96:97]
	v_lshl_add_u64 v[30:31], v[66:67], 0, v[40:41]
	v_mov_b64_e32 v[80:81], v[98:99]
	v_mov_b64_e32 v[82:83], v[100:101]
	v_mov_b32_e32 v30, v70
	v_mov_b32_e32 v31, v70
	v_pk_mul_f32 v[24:25], v[24:25], v[70:71]
	v_pk_mul_f32 v[26:27], v[26:27], v[30:31]
	v_pk_mul_f32 v[24:25], v[32:33], v[24:25]
	v_pk_mul_f32 v[26:27], v[34:35], v[26:27]
	v_mov_b32_e32 v29, v41
	s_nop 0
	v_pk_add_f32 v[30:31], v[78:79], 1.0 op_sel_hi:[1,0]
	v_pk_add_f32 v[32:33], v[76:77], 1.0 op_sel_hi:[1,0]
	s_nop 0
	v_pk_fma_f32 v[26:27], v[26:27], v[30:31], v[82:83]
	v_pk_fma_f32 v[24:25], v[24:25], v[32:33], v[80:81]
	v_bfe_u32 v32, v26, 16, 1
	v_bfe_u32 v30, v24, 16, 1
	v_bfe_u32 v31, v25, 16, 1
	v_bfe_u32 v33, v27, 16, 1
	v_add3_u32 v24, v24, v30, s25
	v_add3_u32 v26, v26, v32, s25
	v_add3_u32 v25, v25, v31, s25
	v_add3_u32 v27, v27, v33, s25
	v_lshrrev_b32_e32 v24, 16, v24
	v_lshrrev_b32_e32 v26, 16, v26
	v_and_or_b32 v24, v25, s26, v24
	v_and_or_b32 v25, v27, s26, v26
	v_lshl_add_u64 v[26:27], v[60:61], 0, v[28:29]
	global_store_dwordx2 v[26:27], v[24:25], off
.LBB0_1455:
	s_or_b64 exec, exec, s[2:3]
	v_lshlrev_b32_e32 v32, 2, v44
	v_mov_b32_e32 v33, v41
	v_mov_b64_e32 v[24:25], v[102:103]
	v_mov_b64_e32 v[26:27], v[104:105]
	v_lshl_add_u64 v[30:31], v[64:65], 0, v[32:33]
	v_mov_b64_e32 v[76:77], v[106:107]
	v_mov_b64_e32 v[78:79], v[108:109]
	v_mov_b64_e32 v[80:81], v[110:111]
	v_mov_b64_e32 v[82:83], v[112:113]
	v_mov_b32_e32 v73, v72
	v_mov_b32_e32 v30, v72
	v_mov_b32_e32 v31, v72
	v_pk_mul_f32 v[22:23], v[22:23], v[30:31]
	v_pk_mul_f32 v[20:21], v[20:21], v[72:73]
	s_nop 0
	v_pk_mul_f32 v[22:23], v[22:23], v[26:27]
	v_pk_mul_f32 v[20:21], v[20:21], v[24:25]
	s_nop 0
	v_pk_add_f32 v[34:35], v[78:79], 1.0 op_sel_hi:[1,0]
	v_pk_add_f32 v[76:77], v[76:77], 1.0 op_sel_hi:[1,0]
	s_nop 0
	v_pk_fma_f32 v[22:23], v[22:23], v[34:35], v[82:83]
	v_pk_fma_f32 v[20:21], v[20:21], v[76:77], v[80:81]
	v_bfe_u32 v35, v22, 16, 1
	v_bfe_u32 v29, v20, 16, 1
	v_bfe_u32 v34, v21, 16, 1
	v_bfe_u32 v37, v23, 16, 1
	v_add3_u32 v20, v20, v29, s25
	v_add3_u32 v22, v22, v35, s25
	v_add3_u32 v21, v21, v34, s25
	v_add3_u32 v23, v23, v37, s25
	v_lshrrev_b32_e32 v20, 16, v20
	v_lshrrev_b32_e32 v22, 16, v22
	v_and_or_b32 v20, v21, s26, v20
	v_and_or_b32 v21, v23, s26, v22
	global_store_dwordx2 v[56:57], v[20:21], off offset:512
	s_and_saveexec_b64 s[2:3], vcc
	s_cbranch_execz .LBB0_1457
	v_lshl_add_u64 v[20:21], v[68:69], 0, v[32:33]
	v_mov_b64_e32 v[20:21], v[114:115]
	v_mov_b64_e32 v[22:23], v[116:117]
	v_lshl_add_u64 v[32:33], v[66:67], 0, v[40:41]
	v_mov_b64_e32 v[32:33], v[118:119]
	v_mov_b64_e32 v[34:35], v[120:121]
	v_mov_b32_e32 v76, v70
	v_mov_b32_e32 v77, v70
	v_pk_mul_f32 v[16:17], v[16:17], v[70:71]
	v_pk_mul_f32 v[18:19], v[18:19], v[76:77]
	v_pk_mul_f32 v[16:17], v[16:17], v[24:25]
	v_pk_mul_f32 v[18:19], v[18:19], v[26:27]
	v_mov_b32_e32 v29, v41
	s_nop 0
	v_pk_add_f32 v[22:23], v[22:23], 1.0 op_sel_hi:[1,0]
	v_pk_add_f32 v[20:21], v[20:21], 1.0 op_sel_hi:[1,0]
	s_nop 0
	v_pk_fma_f32 v[18:19], v[18:19], v[22:23], v[34:35]
	v_pk_fma_f32 v[16:17], v[16:17], v[20:21], v[32:33]
	v_bfe_u32 v22, v18, 16, 1
	v_bfe_u32 v20, v16, 16, 1
	v_bfe_u32 v21, v17, 16, 1
	v_bfe_u32 v23, v19, 16, 1
	v_add3_u32 v16, v16, v20, s25
	v_add3_u32 v18, v18, v22, s25
	v_add3_u32 v17, v17, v21, s25
	v_add3_u32 v19, v19, v23, s25
	v_lshrrev_b32_e32 v16, 16, v16
	v_lshrrev_b32_e32 v18, 16, v18
	v_and_or_b32 v16, v17, s26, v16
	v_and_or_b32 v17, v19, s26, v18
	v_lshl_add_u64 v[18:19], v[60:61], 0, v[28:29]
	global_store_dwordx2 v[18:19], v[16:17], off offset:512
.LBB0_1457:
	s_or_b64 exec, exec, s[2:3]
	v_lshlrev_b32_e32 v20, 2, v48
	v_mov_b32_e32 v21, v41
	v_mov_b64_e32 v[16:17], v[122:123]
	v_mov_b64_e32 v[18:19], v[124:125]
	v_lshl_add_u64 v[22:23], v[64:65], 0, v[20:21]
	v_mov_b64_e32 v[22:23], v[126:127]
	v_mov_b64_e32 v[24:25], v[128:129]
	s_nop 0
	v_mov_b64_e32 v[32:33], v[130:131]
	v_mov_b64_e32 v[34:35], v[132:133]
	v_pk_mul_f32 v[14:15], v[14:15], v[30:31]
	v_pk_mul_f32 v[12:13], v[12:13], v[72:73]
	s_nop 0
	v_pk_mul_f32 v[14:15], v[14:15], v[18:19]
	v_pk_mul_f32 v[12:13], v[12:13], v[16:17]
	s_nop 0
	v_pk_add_f32 v[24:25], v[24:25], 1.0 op_sel_hi:[1,0]
	v_pk_add_f32 v[22:23], v[22:23], 1.0 op_sel_hi:[1,0]
	s_nop 0
	v_pk_fma_f32 v[14:15], v[14:15], v[24:25], v[34:35]
	v_pk_fma_f32 v[12:13], v[12:13], v[22:23], v[32:33]
	v_bfe_u32 v24, v14, 16, 1
	v_bfe_u32 v22, v12, 16, 1
	v_bfe_u32 v23, v13, 16, 1
	v_bfe_u32 v25, v15, 16, 1
	v_add3_u32 v12, v12, v22, s25
	v_add3_u32 v14, v14, v24, s25
	v_add3_u32 v13, v13, v23, s25
	v_add3_u32 v15, v15, v25, s25
	v_lshrrev_b32_e32 v12, 16, v12
	v_lshrrev_b32_e32 v14, 16, v14
	v_and_or_b32 v12, v13, s26, v12
	v_and_or_b32 v13, v15, s26, v14
	global_store_dwordx2 v[56:57], v[12:13], off offset:1024
	s_and_saveexec_b64 s[2:3], vcc
	s_cbranch_execz .LBB0_1459
	v_lshl_add_u64 v[12:13], v[68:69], 0, v[20:21]
	v_mov_b64_e32 v[12:13], v[134:135]
	v_mov_b64_e32 v[14:15], v[136:137]
	v_lshl_add_u64 v[20:21], v[66:67], 0, v[40:41]
	v_mov_b64_e32 v[20:21], v[138:139]
	v_mov_b64_e32 v[22:23], v[140:141]
	v_mov_b32_e32 v24, v70
	v_mov_b32_e32 v25, v70
	v_pk_mul_f32 v[8:9], v[8:9], v[70:71]
	v_pk_mul_f32 v[10:11], v[10:11], v[24:25]
	v_pk_mul_f32 v[8:9], v[8:9], v[16:17]
	v_pk_mul_f32 v[10:11], v[10:11], v[18:19]
	v_mov_b32_e32 v29, v41
	s_nop 0
	v_pk_add_f32 v[14:15], v[14:15], 1.0 op_sel_hi:[1,0]
	v_pk_add_f32 v[12:13], v[12:13], 1.0 op_sel_hi:[1,0]
	s_nop 0
	v_pk_fma_f32 v[10:11], v[10:11], v[14:15], v[22:23]
	v_pk_fma_f32 v[8:9], v[8:9], v[12:13], v[20:21]
	v_bfe_u32 v14, v10, 16, 1
	v_bfe_u32 v12, v8, 16, 1
	v_bfe_u32 v13, v9, 16, 1
	v_bfe_u32 v15, v11, 16, 1
	v_add3_u32 v8, v8, v12, s25
	v_add3_u32 v10, v10, v14, s25
	v_add3_u32 v9, v9, v13, s25
	v_add3_u32 v11, v11, v15, s25
	v_lshrrev_b32_e32 v8, 16, v8
	v_lshrrev_b32_e32 v10, 16, v10
	v_and_or_b32 v8, v9, s26, v8
	v_and_or_b32 v9, v11, s26, v10
	v_lshl_add_u64 v[10:11], v[60:61], 0, v[28:29]
	global_store_dwordx2 v[10:11], v[8:9], off offset:1024
.LBB0_1459:
	s_or_b64 exec, exec, s[2:3]
	v_lshlrev_b32_e32 v12, 2, v52
	v_mov_b32_e32 v13, v41
	v_mov_b64_e32 v[8:9], v[142:143]
	v_mov_b64_e32 v[10:11], v[144:145]
	v_lshl_add_u64 v[14:15], v[64:65], 0, v[12:13]
	v_mov_b64_e32 v[14:15], v[146:147]
	v_mov_b64_e32 v[16:17], v[148:149]
	s_nop 0
	v_mov_b64_e32 v[18:19], v[150:151]
	v_mov_b64_e32 v[20:21], v[152:153]
	v_mov_b32_e32 v22, v72
	v_mov_b32_e32 v23, v72
	v_pk_mul_f32 v[4:5], v[4:5], v[72:73]
	v_pk_mul_f32 v[6:7], v[6:7], v[22:23]
	s_nop 0
	v_pk_mul_f32 v[4:5], v[4:5], v[8:9]
	v_pk_mul_f32 v[6:7], v[6:7], v[10:11]
	s_nop 0
	v_pk_add_f32 v[16:17], v[16:17], 1.0 op_sel_hi:[1,0]
	v_pk_add_f32 v[14:15], v[14:15], 1.0 op_sel_hi:[1,0]
	s_nop 0
	v_pk_fma_f32 v[6:7], v[6:7], v[16:17], v[20:21]
	v_pk_fma_f32 v[4:5], v[4:5], v[14:15], v[18:19]
	v_bfe_u32 v16, v6, 16, 1
	v_bfe_u32 v14, v4, 16, 1
	v_bfe_u32 v15, v5, 16, 1
	v_bfe_u32 v17, v7, 16, 1
	v_add3_u32 v4, v4, v14, s25
	v_add3_u32 v6, v6, v16, s25
	v_add3_u32 v5, v5, v15, s25
	v_add3_u32 v7, v7, v17, s25
	v_lshrrev_b32_e32 v4, 16, v4
	v_lshrrev_b32_e32 v6, 16, v6
	v_and_or_b32 v4, v5, s26, v4
	v_and_or_b32 v5, v7, s26, v6
	global_store_dwordx2 v[56:57], v[4:5], off offset:1536
	s_and_saveexec_b64 s[2:3], vcc
	s_cbranch_execz .LBB0_1448
	v_lshl_add_u64 v[4:5], v[68:69], 0, v[12:13]
	v_mov_b64_e32 v[4:5], v[154:155]
	v_mov_b64_e32 v[6:7], v[156:157]
	v_lshl_add_u64 v[12:13], v[66:67], 0, v[40:41]
	v_mov_b64_e32 v[12:13], v[158:159]
	v_mov_b64_e32 v[14:15], v[160:161]
	v_mov_b32_e32 v16, v70
	v_mov_b32_e32 v17, v70
	v_pk_mul_f32 v[0:1], v[0:1], v[70:71]
	v_pk_mul_f32 v[2:3], v[2:3], v[16:17]
	v_pk_mul_f32 v[0:1], v[0:1], v[8:9]
	v_pk_mul_f32 v[2:3], v[2:3], v[10:11]
	v_mov_b32_e32 v29, v41
	s_nop 0
	v_pk_add_f32 v[6:7], v[6:7], 1.0 op_sel_hi:[1,0]
	v_pk_add_f32 v[4:5], v[4:5], 1.0 op_sel_hi:[1,0]
	s_nop 0
	v_pk_fma_f32 v[2:3], v[2:3], v[6:7], v[14:15]
	v_pk_fma_f32 v[0:1], v[0:1], v[4:5], v[12:13]
	v_bfe_u32 v6, v2, 16, 1
	v_bfe_u32 v4, v0, 16, 1
	v_bfe_u32 v5, v1, 16, 1
	v_bfe_u32 v7, v3, 16, 1
	v_add3_u32 v0, v0, v4, s25
	v_add3_u32 v2, v2, v6, s25
	v_add3_u32 v1, v1, v5, s25
	v_add3_u32 v3, v3, v7, s25
	v_lshrrev_b32_e32 v0, 16, v0
	v_lshrrev_b32_e32 v2, 16, v2
	v_and_or_b32 v0, v1, s26, v0
	v_and_or_b32 v1, v3, s26, v2
	v_lshl_add_u64 v[2:3], v[60:61], 0, v[28:29]
	global_store_dwordx2 v[2:3], v[0:1], off offset:1536
	s_branch .LBB0_1448

.LBB0_2213:
	v_add_u32_e32 v0, s19, v36
	v_cmp_gt_i32_e32 vcc, s13, v0
	s_nop 1
	v_cndmask_b32_e32 v60, v36, v0, vcc
	v_mul_hi_i32 v0, v60, s9
	v_lshrrev_b32_e32 v1, 31, v0
	v_ashrrev_i32_e32 v0, 11, v0
	v_add_u32_e32 v2, v0, v1
	v_mad_i32_i24 v4, v2, s25, v60
	v_cmp_lt_i32_e32 vcc, s26, v4
	v_ashrrev_i32_e32 v3, 31, v2
	s_and_saveexec_b64 s[2:3], vcc
	s_xor_b64 s[2:3], exec, s[2:3]
	v_add_u32_e32 v40, 0xffffff00, v4
	v_lshlrev_b64 v[0:1], 24, v[2:3]
	v_lshl_add_u64 v[0:1], s[72:73], 0, v[0:1]
	v_lshlrev_b64 v[4:5], 12, v[40:41]
	v_lshl_add_u64 v[0:1], v[0:1], 0, v[4:5]
	v_mul_hi_i32_i24_e32 v67, 0x1800, v2
	v_mul_i32_i24_e32 v66, 0x1800, v2
	s_andn2_saveexec_b64 s[2:3], s[2:3]
	v_ashrrev_i32_e32 v5, 31, v4
	v_lshlrev_b64 v[0:1], 20, v[2:3]
	v_lshl_add_u64 v[0:1], s[10:11], 0, v[0:1]
	v_lshlrev_b64 v[2:3], 12, v[4:5]
	v_lshl_add_u64 v[0:1], v[0:1], 0, v[2:3]
	v_mov_b64_e32 v[66:67], 0xc000
	s_or_b64 exec, exec, s[2:3]
	v_mul_hi_i32 v4, v36, s9
	v_lshlrev_b32_e32 v40, 2, v38
	v_lshl_add_u64 v[0:1], v[0:1], 0, v[40:41]
	v_lshrrev_b32_e32 v5, 31, v4
	v_ashrrev_i32_e32 v4, 11, v4
	global_load_dwordx4 v[24:27], v[0:1], off nt
	v_add_u32_e32 v62, v4, v5
	v_mad_i32_i24 v6, v62, s25, v36
	global_load_dwordx4 v[16:19], v[0:1], off offset:1024 nt
	global_load_dwordx4 v[8:11], v[0:1], off offset:2048 nt
	s_nop 0
	global_load_dwordx4 v[0:3], v[0:1], off offset:3072 nt
	v_add_u32_e32 v12, 0xffffff00, v6
	v_mov_b32_e32 v4, s73
	v_mov_b32_e32 v5, s11
	v_cmp_gt_i32_e32 vcc, s24, v6
	v_ashrrev_i32_e32 v63, 31, v62
	v_ashrrev_i32_e32 v7, 31, v6
	v_cndmask_b32_e32 v5, v4, v5, vcc
	v_mov_b32_e32 v4, s72
	v_mov_b32_e32 v13, s10
	v_cndmask_b32_e32 v6, v12, v6, vcc
	v_cndmask_b32_e64 v12, 24, 20, vcc
	v_cndmask_b32_e32 v4, v4, v13, vcc
	v_cndmask_b32_e32 v7, 0, v7, vcc
	v_lshlrev_b64 v[12:13], v12, v[62:63]
	v_lshl_add_u64 v[4:5], v[4:5], 0, v[12:13]
	v_lshlrev_b64 v[6:7], 12, v[6:7]
	v_lshl_add_u64 v[4:5], v[4:5], 0, v[6:7]
	v_lshl_add_u64 v[12:13], v[4:5], 0, v[40:41]
	global_load_dwordx4 v[28:31], v[12:13], off nt
	global_load_dwordx4 v[20:23], v[12:13], off offset:1024 nt
	global_load_dwordx4 v[4:7], v[12:13], off offset:3072 nt
	s_nop 0
	global_load_dwordx4 v[12:15], v[12:13], off offset:2048 nt
	s_nop 0
	global_load_dwordx4 v[32:35], v[42:43], off
	v_cndmask_b32_e64 v37, v62, 8, vcc
	v_mul_hi_i32_i24_e32 v63, 0x6000, v37
	v_mul_i32_i24_e32 v62, 0x6000, v37
	v_lshl_add_u64 v[64:65], s[56:57], 0, v[62:63]
	v_lshl_add_u64 v[62:63], v[64:65], 0, s[20:21]
	v_lshl_add_u64 v[64:65], v[64:65], 0, s[22:23]
	v_lshl_add_u64 v[68:69], v[62:63], 0, v[40:41]
	v_lshl_add_u64 v[70:71], v[64:65], 0, v[40:41]
	global_load_dwordx4 v[76:79], v[68:69], off
	global_load_dwordx4 v[80:83], v[70:71], off
	v_cmp_ne_u32_e32 vcc, v36, v60
	s_waitcnt vmcnt(0)
	v_pk_mul_f32 v[68:69], v[26:27], v[26:27]
	v_pk_mul_f32 v[70:71], v[24:25], v[24:25]
	v_pk_mul_f32 v[72:73], v[18:19], v[18:19]
	v_pk_mul_f32 v[84:85], v[16:17], v[16:17]
	v_pk_mov_b32 v[90:91], v[70:71], v[68:69] op_sel:[1,0]
	v_mov_b32_e32 v71, v69
	v_pk_mov_b32 v[68:69], v[84:85], v[72:73] op_sel:[1,0]
	v_mov_b32_e32 v85, v73
	v_mul_f32_e32 v89, v3, v3
	v_mul_f32_e32 v86, v9, v9
	v_mul_f32_e32 v88, v11, v11
	v_pk_add_f32 v[70:71], v[90:91], v[70:71]
	v_pk_add_f32 v[68:69], v[68:69], v[84:85]
	v_mul_f32_e32 v37, v0, v0
	v_mul_f32_e32 v61, v1, v1
	v_mul_f32_e32 v75, v2, v2
	v_pk_fma_f32 v[72:73], v[8:9], v[8:9], v[86:87] op_sel_hi:[1,1,0]
	v_pk_fma_f32 v[86:87], v[10:11], v[10:11], v[88:89] op_sel_hi:[1,1,0]
	v_pk_add_f32 v[70:71], v[70:71], v[70:71] op_sel:[0,1] op_sel_hi:[1,0]
	v_pk_add_f32 v[68:69], v[68:69], v[68:69] op_sel:[0,1] op_sel_hi:[1,0]
	v_mov_b32_e32 v73, v75
	v_mov_b32_e32 v87, v89
	v_mov_b32_e32 v71, v37
	v_mov_b32_e32 v69, v61
	v_pk_add_f32 v[72:73], v[72:73], v[86:87]
	v_pk_add_f32 v[68:69], v[70:71], v[68:69]
	v_pk_mul_f32 v[70:71], v[30:31], v[30:31]
	v_pk_mul_f32 v[84:85], v[28:29], v[28:29]
	v_pk_mul_f32 v[86:87], v[22:23], v[22:23]
	v_pk_mul_f32 v[88:89], v[20:21], v[20:21]
	v_pk_mov_b32 v[94:95], v[84:85], v[70:71] op_sel:[1,0]
	v_mov_b32_e32 v85, v71
	v_pk_mov_b32 v[70:71], v[88:89], v[86:87] op_sel:[1,0]
	v_mov_b32_e32 v89, v87
	v_mul_f32_e32 v93, v7, v7
	v_mul_f32_e32 v90, v13, v13
	v_mul_f32_e32 v92, v15, v15
	v_pk_add_f32 v[84:85], v[94:95], v[84:85]
	v_pk_add_f32 v[70:71], v[70:71], v[88:89]
	v_mul_f32_e32 v37, v4, v4
	v_mul_f32_e32 v61, v5, v5
	v_mul_f32_e32 v75, v6, v6
	v_pk_fma_f32 v[86:87], v[12:13], v[12:13], v[90:91] op_sel_hi:[1,1,0]
	v_pk_fma_f32 v[90:91], v[14:15], v[14:15], v[92:93] op_sel_hi:[1,1,0]
	v_pk_add_f32 v[84:85], v[84:85], v[84:85] op_sel:[0,1] op_sel_hi:[1,0]
	v_pk_add_f32 v[70:71], v[70:71], v[70:71] op_sel:[0,1] op_sel_hi:[1,0]
	v_mov_b32_e32 v87, v75
	v_mov_b32_e32 v91, v93
	v_mov_b32_e32 v85, v37
	v_mov_b32_e32 v71, v61
	v_pk_add_f32 v[86:87], v[86:87], v[90:91]
	v_pk_add_f32 v[70:71], v[84:85], v[70:71]
	v_pk_add_f32 v[68:69], v[68:69], v[72:73]
	v_pk_add_f32 v[70:71], v[70:71], v[86:87]
	v_mov_b32_e32 v72, v68
	v_mov_b32_e32 v73, v70
	v_mov_b32_e32 v70, v69
	v_pk_add_f32 v[68:69], v[72:73], v[70:71]
	v_lshl_add_u64 v[170:171], v[66:67],2,s[56:57]
	v_lshl_add_u64 v[172:173], v[170:171],0,s[22:23]
	v_lshl_add_u64 v[174:175], v[172:173],0,v[40:41]
	global_load_dwordx4 v[96:99], v[174:175], off
	v_lshl_add_u64 v[170:171], v[66:67],2,s[56:57]
	v_lshl_add_u64 v[172:173], v[170:171],0,s[20:21]
	v_lshl_add_u64 v[174:175], v[172:173],0,v[40:41]
	global_load_dwordx4 v[100:103], v[174:175], off
	global_load_dwordx4 v[104:107], v[46:47], off
	v_lshlrev_b32_e32 v170, 2,v44
	v_mov_b32_e32 v171, v41
	v_lshl_add_u64 v[172:173], v[64:65],0,v[170:171]
	global_load_dwordx4 v[108:111], v[172:173], off
	v_lshlrev_b32_e32 v170, 2,v44
	v_mov_b32_e32 v171, v41
	v_lshl_add_u64 v[172:173], v[62:63],0,v[170:171]
	global_load_dwordx4 v[112:115], v[172:173], off
	v_lshl_add_u64 v[170:171], v[66:67],2,s[56:57]
	v_lshl_add_u64 v[172:173], v[170:171],0,s[22:23]
	v_lshlrev_b32_e32 v174, 2,v44
	v_mov_b32_e32 v175, v41
	v_lshl_add_u64 v[176:177], v[172:173],0,v[174:175]
	global_load_dwordx4 v[116:119], v[176:177], off
	v_lshl_add_u64 v[170:171], v[66:67],2,s[56:57]
	v_lshl_add_u64 v[172:173], v[170:171],0,s[20:21]
	v_lshlrev_b32_e32 v174, 2,v44
	v_mov_b32_e32 v175, v41
	v_lshl_add_u64 v[176:177], v[172:173],0,v[174:175]
	global_load_dwordx4 v[120:123], v[176:177], off
	global_load_dwordx4 v[124:127], v[50:51], off
	v_lshlrev_b32_e32 v170, 2,v48
	v_mov_b32_e32 v171, v41
	v_lshl_add_u64 v[172:173], v[64:65],0,v[170:171]
	global_load_dwordx4 v[128:131], v[172:173], off
	v_lshlrev_b32_e32 v170, 2,v48
	v_mov_b32_e32 v171, v41
	v_lshl_add_u64 v[172:173], v[62:63],0,v[170:171]
	global_load_dwordx4 v[132:135], v[172:173], off
	v_lshl_add_u64 v[170:171], v[66:67],2,s[56:57]
	v_lshl_add_u64 v[172:173], v[170:171],0,s[22:23]
	v_lshlrev_b32_e32 v174, 2,v48
	v_mov_b32_e32 v175, v41
	v_lshl_add_u64 v[176:177], v[172:173],0,v[174:175]
	global_load_dwordx4 v[136:139], v[176:177], off
	v_lshl_add_u64 v[170:171], v[66:67],2,s[56:57]
	v_lshl_add_u64 v[172:173], v[170:171],0,s[20:21]
	v_lshlrev_b32_e32 v174, 2,v48
	v_mov_b32_e32 v175, v41
	v_lshl_add_u64 v[176:177], v[172:173],0,v[174:175]
	global_load_dwordx4 v[140:143], v[176:177], off
	global_load_dwordx4 v[144:147], v[54:55], off
	v_lshlrev_b32_e32 v170, 2,v52
	v_mov_b32_e32 v171, v41
	v_lshl_add_u64 v[172:173], v[64:65],0,v[170:171]
	global_load_dwordx4 v[148:151], v[172:173], off
	v_lshlrev_b32_e32 v170, 2,v52
	v_mov_b32_e32 v171, v41
	v_lshl_add_u64 v[172:173], v[62:63],0,v[170:171]
	global_load_dwordx4 v[152:155], v[172:173], off
	v_lshl_add_u64 v[170:171], v[66:67],2,s[56:57]
	v_lshl_add_u64 v[172:173], v[170:171],0,s[22:23]
	v_lshlrev_b32_e32 v174, 2,v52
	v_mov_b32_e32 v175, v41
	v_lshl_add_u64 v[176:177], v[172:173],0,v[174:175]
	global_load_dwordx4 v[156:159], v[176:177], off
	v_lshl_add_u64 v[170:171], v[66:67],2,s[56:57]
	v_lshl_add_u64 v[172:173], v[170:171],0,s[20:21]
	v_lshlrev_b32_e32 v174, 2,v52
	v_mov_b32_e32 v175, v41
	v_lshl_add_u64 v[176:177], v[172:173],0,v[174:175]
	global_load_dwordx4 v[160:163], v[176:177], off
	ds_bpermute_b32 v71, v39, v69
	ds_bpermute_b32 v70, v39, v68
	v_lshl_add_u64 v[72:73], v[66:67], 2, s[56:57]
	v_lshl_add_u64 v[66:67], v[72:73], 0, s[20:21]
	v_pk_add_f32 v[80:81], v[80:81], 1.0 op_sel_hi:[1,0]
	v_pk_add_f32 v[82:83], v[82:83], 1.0 op_sel_hi:[1,0]
	s_waitcnt lgkmcnt(0)
	v_pk_add_f32 v[68:69], v[68:69], v[70:71]
	ds_bpermute_b32 v71, v45, v69
	ds_bpermute_b32 v70, v45, v68
	v_ashrrev_i32_e32 v61, 31, v60
	v_lshlrev_b64 v[60:61], 11, v[60:61]
	v_lshl_add_u64 v[60:61], s[54:55], 0, v[60:61]
	s_waitcnt lgkmcnt(0)
	v_pk_add_f32 v[68:69], v[68:69], v[70:71]
	ds_bpermute_b32 v71, v49, v69
	ds_bpermute_b32 v70, v49, v68
	s_waitcnt lgkmcnt(0)
	v_pk_add_f32 v[68:69], v[68:69], v[70:71]
	ds_bpermute_b32 v71, v53, v69
	ds_bpermute_b32 v70, v53, v68
	s_waitcnt lgkmcnt(0)
	v_pk_add_f32 v[68:69], v[68:69], v[70:71]
	ds_bpermute_b32 v71, v59, v69
	ds_bpermute_b32 v70, v59, v68
	s_waitcnt lgkmcnt(0)
	v_pk_add_f32 v[70:71], v[68:69], v[70:71]
	ds_bpermute_b32 v85, v74, v71
	ds_bpermute_b32 v84, v74, v70
	v_lshl_add_u64 v[68:69], v[72:73], 0, s[22:23]
	s_waitcnt lgkmcnt(0)
	s_waitcnt vmcnt(0)
	v_pk_add_f32 v[70:71], v[70:71], v[84:85]
	s_nop 0
	v_pk_fma_f32 v[70:71], v[70:71], s[18:19], v[58:59] op_sel_hi:[1,0,0]
	s_nop 0
	v_mul_f32_e32 v37, 0x4b800000, v71
	v_cmp_gt_f32_e64 s[2:3], s27, v71
	v_mul_f32_e32 v72, 0x4b800000, v70
	v_cmp_gt_f32_e64 s[4:5], s27, v70
	v_cndmask_b32_e64 v37, v71, v37, s[2:3]
	v_rsq_f32_e32 v37, v37
	v_cndmask_b32_e64 v70, v70, v72, s[4:5]
	v_rsq_f32_e32 v70, v70
	v_mul_f32_e32 v71, 0x45800000, v37
	v_cndmask_b32_e64 v72, v37, v71, s[2:3]
	v_mul_f32_e32 v73, 0x45800000, v70
	v_pk_mul_f32 v[28:29], v[28:29], v[72:73] op_sel_hi:[1,0]
	v_pk_mul_f32 v[30:31], v[30:31], v[72:73] op_sel_hi:[1,0]
	v_pk_mul_f32 v[28:29], v[32:33], v[28:29]
	v_pk_mul_f32 v[30:31], v[34:35], v[30:31]
	v_pk_fma_f32 v[28:29], v[80:81], v[28:29], v[76:77]
	v_pk_fma_f32 v[30:31], v[82:83], v[30:31], v[78:79]
	v_bfe_u32 v37, v28, 16, 1
	v_add3_u32 v28, v28, v37, s28
	v_bfe_u32 v37, v29, 16, 1
	v_lshrrev_b32_e32 v28, 16, v28
	v_add3_u32 v29, v29, v37, s28
	v_and_or_b32 v28, v29, s29, v28
	v_bfe_u32 v29, v30, 16, 1
	v_add3_u32 v29, v30, v29, s28
	v_bfe_u32 v30, v31, 16, 1
	v_lshrrev_b32_e32 v29, 16, v29
	v_add3_u32 v30, v31, v30, s28
	v_cndmask_b32_e64 v70, v70, v73, s[4:5]
	v_and_or_b32 v29, v30, s29, v29
	v_mov_b32_e32 v71, v70
	global_store_dwordx2 v[56:57], v[28:29], off
	v_lshlrev_b32_e32 v28, 1, v38
	s_and_saveexec_b64 s[2:3], vcc
	s_cbranch_execz .LBB0_2219
	v_lshl_add_u64 v[30:31], v[68:69], 0, v[40:41]
	v_mov_b64_e32 v[76:77], v[96:97]
	v_mov_b64_e32 v[78:79], v[98:99]
	v_lshl_add_u64 v[30:31], v[66:67], 0, v[40:41]
	v_mov_b64_e32 v[80:81], v[100:101]
	v_mov_b64_e32 v[82:83], v[102:103]
	v_mov_b32_e32 v30, v70
	v_mov_b32_e32 v31, v70
	v_pk_mul_f32 v[24:25], v[24:25], v[70:71]
	v_pk_mul_f32 v[26:27], v[26:27], v[30:31]
	v_pk_mul_f32 v[24:25], v[32:33], v[24:25]
	v_pk_mul_f32 v[26:27], v[34:35], v[26:27]
	v_mov_b32_e32 v29, v41
	s_nop 0
	v_pk_add_f32 v[30:31], v[78:79], 1.0 op_sel_hi:[1,0]
	v_pk_add_f32 v[32:33], v[76:77], 1.0 op_sel_hi:[1,0]
	s_nop 0
	v_pk_fma_f32 v[26:27], v[26:27], v[30:31], v[82:83]
	v_pk_fma_f32 v[24:25], v[24:25], v[32:33], v[80:81]
	v_bfe_u32 v32, v26, 16, 1
	v_bfe_u32 v30, v24, 16, 1
	v_bfe_u32 v31, v25, 16, 1
	v_bfe_u32 v33, v27, 16, 1
	v_add3_u32 v24, v24, v30, s28
	v_add3_u32 v26, v26, v32, s28
	v_add3_u32 v25, v25, v31, s28
	v_add3_u32 v27, v27, v33, s28
	v_lshrrev_b32_e32 v24, 16, v24
	v_lshrrev_b32_e32 v26, 16, v26
	v_and_or_b32 v24, v25, s29, v24
	v_and_or_b32 v25, v27, s29, v26
	v_lshl_add_u64 v[26:27], v[60:61], 0, v[28:29]
	global_store_dwordx2 v[26:27], v[24:25], off
.LBB0_2219:
	s_or_b64 exec, exec, s[2:3]
	v_lshlrev_b32_e32 v40, 2, v44
	v_lshl_add_u64 v[30:31], v[64:65], 0, v[40:41]
	v_mov_b64_e32 v[24:25], v[104:105]
	v_mov_b64_e32 v[26:27], v[106:107]
	v_mov_b64_e32 v[32:33], v[108:109]
	v_mov_b64_e32 v[34:35], v[110:111]
	v_lshl_add_u64 v[30:31], v[62:63], 0, v[40:41]
	v_mov_b64_e32 v[76:77], v[112:113]
	v_mov_b64_e32 v[78:79], v[114:115]
	v_mov_b32_e32 v73, v72
	v_mov_b32_e32 v30, v72
	v_mov_b32_e32 v31, v72
	v_pk_mul_f32 v[22:23], v[22:23], v[30:31]
	v_pk_mul_f32 v[20:21], v[20:21], v[72:73]
	s_nop 0
	v_pk_mul_f32 v[22:23], v[22:23], v[26:27]
	v_pk_mul_f32 v[20:21], v[20:21], v[24:25]
	s_nop 0
	v_pk_add_f32 v[34:35], v[34:35], 1.0 op_sel_hi:[1,0]
	v_pk_add_f32 v[32:33], v[32:33], 1.0 op_sel_hi:[1,0]
	s_nop 0
	v_pk_fma_f32 v[22:23], v[22:23], v[34:35], v[78:79]
	v_pk_fma_f32 v[20:21], v[20:21], v[32:33], v[76:77]
	v_bfe_u32 v33, v22, 16, 1
	v_bfe_u32 v29, v20, 16, 1
	v_bfe_u32 v32, v21, 16, 1
	v_bfe_u32 v34, v23, 16, 1
	v_add3_u32 v20, v20, v29, s28
	v_add3_u32 v22, v22, v33, s28
	v_add3_u32 v21, v21, v32, s28
	v_add3_u32 v23, v23, v34, s28
	v_lshrrev_b32_e32 v20, 16, v20
	v_lshrrev_b32_e32 v22, 16, v22
	v_and_or_b32 v20, v21, s29, v20
	v_and_or_b32 v21, v23, s29, v22
	global_store_dwordx2 v[56:57], v[20:21], off offset:512
	s_and_saveexec_b64 s[2:3], vcc
	s_cbranch_execz .LBB0_2221
	v_lshl_add_u64 v[20:21], v[68:69], 0, v[40:41]
	v_mov_b64_e32 v[20:21], v[116:117]
	v_mov_b64_e32 v[22:23], v[118:119]
	v_lshl_add_u64 v[32:33], v[66:67], 0, v[40:41]
	v_mov_b64_e32 v[32:33], v[120:121]
	v_mov_b64_e32 v[34:35], v[122:123]
	v_mov_b32_e32 v76, v70
	v_mov_b32_e32 v77, v70
	v_pk_mul_f32 v[16:17], v[16:17], v[70:71]
	v_pk_mul_f32 v[18:19], v[18:19], v[76:77]
	v_pk_mul_f32 v[16:17], v[16:17], v[24:25]
	v_pk_mul_f32 v[18:19], v[18:19], v[26:27]
	v_mov_b32_e32 v29, v41
	s_nop 0
	v_pk_add_f32 v[22:23], v[22:23], 1.0 op_sel_hi:[1,0]
	v_pk_add_f32 v[20:21], v[20:21], 1.0 op_sel_hi:[1,0]
	s_nop 0
	v_pk_fma_f32 v[18:19], v[18:19], v[22:23], v[34:35]
	v_pk_fma_f32 v[16:17], v[16:17], v[20:21], v[32:33]
	v_bfe_u32 v22, v18, 16, 1
	v_bfe_u32 v20, v16, 16, 1
	v_bfe_u32 v21, v17, 16, 1
	v_bfe_u32 v23, v19, 16, 1
	v_add3_u32 v16, v16, v20, s28
	v_add3_u32 v18, v18, v22, s28
	v_add3_u32 v17, v17, v21, s28
	v_add3_u32 v19, v19, v23, s28
	v_lshrrev_b32_e32 v16, 16, v16
	v_lshrrev_b32_e32 v18, 16, v18
	v_and_or_b32 v16, v17, s29, v16
	v_and_or_b32 v17, v19, s29, v18
	v_lshl_add_u64 v[18:19], v[60:61], 0, v[28:29]
	global_store_dwordx2 v[18:19], v[16:17], off offset:512
.LBB0_2221:
	s_or_b64 exec, exec, s[2:3]
	v_lshlrev_b32_e32 v40, 2, v48
	v_lshl_add_u64 v[20:21], v[64:65], 0, v[40:41]
	v_mov_b64_e32 v[16:17], v[124:125]
	v_mov_b64_e32 v[18:19], v[126:127]
	v_lshl_add_u64 v[24:25], v[62:63], 0, v[40:41]
	v_mov_b64_e32 v[20:21], v[128:129]
	v_mov_b64_e32 v[22:23], v[130:131]
	v_pk_mul_f32 v[14:15], v[14:15], v[30:31]
	v_mov_b64_e32 v[24:25], v[132:133]
	v_mov_b64_e32 v[26:27], v[134:135]
	v_pk_mul_f32 v[12:13], v[12:13], v[72:73]
	s_nop 0
	v_pk_mul_f32 v[14:15], v[14:15], v[18:19]
	v_pk_mul_f32 v[12:13], v[12:13], v[16:17]
	s_nop 0
	v_pk_add_f32 v[22:23], v[22:23], 1.0 op_sel_hi:[1,0]
	v_pk_add_f32 v[20:21], v[20:21], 1.0 op_sel_hi:[1,0]
	s_nop 0
	v_pk_fma_f32 v[14:15], v[14:15], v[22:23], v[26:27]
	v_pk_fma_f32 v[12:13], v[12:13], v[20:21], v[24:25]
	v_bfe_u32 v22, v14, 16, 1
	v_bfe_u32 v20, v12, 16, 1
	v_bfe_u32 v21, v13, 16, 1
	v_bfe_u32 v23, v15, 16, 1
	v_add3_u32 v12, v12, v20, s28
	v_add3_u32 v14, v14, v22, s28
	v_add3_u32 v13, v13, v21, s28
	v_add3_u32 v15, v15, v23, s28
	v_lshrrev_b32_e32 v12, 16, v12
	v_lshrrev_b32_e32 v14, 16, v14
	v_and_or_b32 v12, v13, s29, v12
	v_and_or_b32 v13, v15, s29, v14
	global_store_dwordx2 v[56:57], v[12:13], off offset:1024
	s_and_saveexec_b64 s[2:3], vcc
	s_cbranch_execz .LBB0_2223
	v_lshl_add_u64 v[12:13], v[68:69], 0, v[40:41]
	v_mov_b64_e32 v[12:13], v[136:137]
	v_mov_b64_e32 v[14:15], v[138:139]
	v_lshl_add_u64 v[20:21], v[66:67], 0, v[40:41]
	v_mov_b64_e32 v[20:21], v[140:141]
	v_mov_b64_e32 v[22:23], v[142:143]
	v_mov_b32_e32 v24, v70
	v_mov_b32_e32 v25, v70
	v_pk_mul_f32 v[8:9], v[8:9], v[70:71]
	v_pk_mul_f32 v[10:11], v[10:11], v[24:25]
	v_pk_mul_f32 v[8:9], v[8:9], v[16:17]
	v_pk_mul_f32 v[10:11], v[10:11], v[18:19]
	v_mov_b32_e32 v29, v41
	s_nop 0
	v_pk_add_f32 v[14:15], v[14:15], 1.0 op_sel_hi:[1,0]
	v_pk_add_f32 v[12:13], v[12:13], 1.0 op_sel_hi:[1,0]
	s_nop 0
	v_pk_fma_f32 v[10:11], v[10:11], v[14:15], v[22:23]
	v_pk_fma_f32 v[8:9], v[8:9], v[12:13], v[20:21]
	v_bfe_u32 v14, v10, 16, 1
	v_bfe_u32 v12, v8, 16, 1
	v_bfe_u32 v13, v9, 16, 1
	v_bfe_u32 v15, v11, 16, 1
	v_add3_u32 v8, v8, v12, s28
	v_add3_u32 v10, v10, v14, s28
	v_add3_u32 v9, v9, v13, s28
	v_add3_u32 v11, v11, v15, s28
	v_lshrrev_b32_e32 v8, 16, v8
	v_lshrrev_b32_e32 v10, 16, v10
	v_and_or_b32 v8, v9, s29, v8
	v_and_or_b32 v9, v11, s29, v10
	v_lshl_add_u64 v[10:11], v[60:61], 0, v[28:29]
	global_store_dwordx2 v[10:11], v[8:9], off offset:1024
.LBB0_2223:
	s_or_b64 exec, exec, s[2:3]
	v_lshlrev_b32_e32 v40, 2, v52
	v_lshl_add_u64 v[12:13], v[64:65], 0, v[40:41]
	v_mov_b64_e32 v[8:9], v[144:145]
	v_mov_b64_e32 v[10:11], v[146:147]
	v_lshl_add_u64 v[16:17], v[62:63], 0, v[40:41]
	v_mov_b64_e32 v[12:13], v[148:149]
	v_mov_b64_e32 v[14:15], v[150:151]
	v_mov_b32_e32 v20, v72
	v_mov_b64_e32 v[16:17], v[152:153]
	v_mov_b64_e32 v[18:19], v[154:155]
	v_mov_b32_e32 v21, v72
	v_pk_mul_f32 v[4:5], v[4:5], v[72:73]
	v_pk_mul_f32 v[6:7], v[6:7], v[20:21]
	s_nop 0
	v_pk_mul_f32 v[4:5], v[4:5], v[8:9]
	v_pk_mul_f32 v[6:7], v[6:7], v[10:11]
	s_nop 0
	v_pk_add_f32 v[14:15], v[14:15], 1.0 op_sel_hi:[1,0]
	v_pk_add_f32 v[12:13], v[12:13], 1.0 op_sel_hi:[1,0]
	s_nop 0
	v_pk_fma_f32 v[6:7], v[6:7], v[14:15], v[18:19]
	v_pk_fma_f32 v[4:5], v[4:5], v[12:13], v[16:17]
	v_bfe_u32 v14, v6, 16, 1
	v_bfe_u32 v12, v4, 16, 1
	v_bfe_u32 v13, v5, 16, 1
	v_bfe_u32 v15, v7, 16, 1
	v_add3_u32 v4, v4, v12, s28
	v_add3_u32 v6, v6, v14, s28
	v_add3_u32 v5, v5, v13, s28
	v_add3_u32 v7, v7, v15, s28
	v_lshrrev_b32_e32 v4, 16, v4
	v_lshrrev_b32_e32 v6, 16, v6
	v_and_or_b32 v4, v5, s29, v4
	v_and_or_b32 v5, v7, s29, v6
	global_store_dwordx2 v[56:57], v[4:5], off offset:1536
	s_and_saveexec_b64 s[2:3], vcc
	s_cbranch_execz .LBB0_2212
	v_lshl_add_u64 v[4:5], v[68:69], 0, v[40:41]
	v_mov_b64_e32 v[4:5], v[156:157]
	v_mov_b64_e32 v[6:7], v[158:159]
	v_lshl_add_u64 v[12:13], v[66:67], 0, v[40:41]
	v_mov_b64_e32 v[12:13], v[160:161]
	v_mov_b64_e32 v[14:15], v[162:163]
	v_mov_b32_e32 v16, v70
	v_mov_b32_e32 v17, v70
	v_pk_mul_f32 v[0:1], v[0:1], v[70:71]
	v_pk_mul_f32 v[2:3], v[2:3], v[16:17]
	v_pk_mul_f32 v[0:1], v[0:1], v[8:9]
	v_pk_mul_f32 v[2:3], v[2:3], v[10:11]
	v_mov_b32_e32 v29, v41
	s_nop 0
	v_pk_add_f32 v[6:7], v[6:7], 1.0 op_sel_hi:[1,0]
	v_pk_add_f32 v[4:5], v[4:5], 1.0 op_sel_hi:[1,0]
	s_nop 0
	v_pk_fma_f32 v[2:3], v[2:3], v[6:7], v[14:15]
	v_pk_fma_f32 v[0:1], v[0:1], v[4:5], v[12:13]
	v_bfe_u32 v6, v2, 16, 1
	v_bfe_u32 v4, v0, 16, 1
	v_bfe_u32 v5, v1, 16, 1
	v_bfe_u32 v7, v3, 16, 1
	v_add3_u32 v0, v0, v4, s28
	v_add3_u32 v2, v2, v6, s28
	v_add3_u32 v1, v1, v5, s28
	v_add3_u32 v3, v3, v7, s28
	v_lshrrev_b32_e32 v0, 16, v0
	v_lshrrev_b32_e32 v2, 16, v2
	v_and_or_b32 v0, v1, s29, v0
	v_and_or_b32 v1, v3, s29, v2
	v_lshl_add_u64 v[2:3], v[60:61], 0, v[28:29]
	global_store_dwordx2 v[2:3], v[0:1], off offset:1536
	s_branch .LBB0_2212
